# q rmsnorm+rope moved into the attention prologue (reads raw q from QKV); qkprep reduced to K/V + new_k/new_v only
# speedup vs baseline: 1.0077x; 1.0076x over previous
.LBB0_739:
	s_mov_b64 s[40:41], s[88:89]
	s_load_dwordx4 s[52:55], s[40:41], 0xb0
	s_load_dwordx4 s[48:51], s[40:41], 0x10
	s_waitcnt vmcnt(0)
	v_mov_b32_e32 v2, v204
	v_readlane_b32 s3, v254, 2
	s_waitcnt lgkmcnt(0)
	s_add_u32 s64, s54, 0x12dc8000
	s_addc_u32 s65, s55, 0
	v_ashrrev_i32_e32 v1, 6, v2
	s_waitcnt vmcnt(8)
	v_and_b32_e32 v4, 63, v2
	s_add_u32 s66, s54, 0x13208000
	v_add_u32_e32 v1, s3, v1
	s_movk_i32 s3, 0x3000
	s_addc_u32 s67, s55, 0
	v_lshlrev_b32_e32 v0, 1, v4
	v_cmp_gt_i32_e32 vcc, s3, v1
	s_and_saveexec_b64 s[68:69], vcc
	s_cbranch_execz .LBB0_766
	s_load_dwordx4 s[44:47], s[88:89], 0x80
	v_readfirstlane_b32 s70, v1
	v_and_b32_e32 v2, 15, v205
	v_bfe_u32 v3, v205, 4, 1
	v_lshrrev_b32_e32 v16, 5, v205
	v_lshlrev_b32_e32 v17, 2, v2
	v_lshl_add_u32 v17, v3, 7, v17
	v_lshl_add_u32 v18, v16, 8, v17
	v_mul_u32_u24_e32 v19, 0x110000, v16
	v_add_u32_e32 v19, v19, v17
	v_lshl_add_u32 v20, v16, 16, v17
	v_lshlrev_b32_e32 v24, 3, v2
	v_lshl_add_u32 v24, v3, 8, v24
	v_lshl_add_u32 v21, v16, 17, v24
	v_lshlrev_b32_e32 v22, 2, v205
	v_lshlrev_b32_e32 v23, 3, v205
	v_lshlrev_b32_e32 v25, 2, v2
	v_cvt_f32_ubyte0_e32 v26, v25
	v_add_u32_e32 v25, 2, v25
	v_cvt_f32_ubyte0_e32 v27, v25
	v_mul_f32_e32 v26, 0xbe549a78, v26
	v_mul_f32_e32 v27, 0xbe549a78, v27
	v_exp_f32_e32 v26, v26
	v_exp_f32_e32 v27, v27
	v_cmp_eq_u32_e64 s[42:43], 0, v3
	s_waitcnt lgkmcnt(0)
	global_load_dwordx2 v[4:5], v24, s[44:45]
	global_load_dwordx2 v[6:7], v24, s[44:45] offset:128
	global_load_dwordx2 v[8:9], v24, s[46:47]
	global_load_dwordx2 v[10:11], v24, s[46:47] offset:128
	s_add_i32 s71, s70, 0x0
	s_mul_i32 s71, s71, 0xc00
	s_add_u32 s71, s71, 0xb7c8000
	s_add_u32 s4, s54, s71
	s_addc_u32 s5, s55, 0
	global_load_dword v108, v18, s[4:5] offset:2048
	global_load_dword v109, v18, s[4:5] offset:2112
	global_load_dword v110, v22, s[4:5] offset:2560
	global_load_dword v111, v22, s[4:5] offset:2816
	s_add_i32 s71, s70, 0x800
	s_mul_i32 s71, s71, 0xc00
	s_add_u32 s71, s71, 0xb7c8000
	s_add_u32 s4, s54, s71
	s_addc_u32 s5, s55, 0
	global_load_dword v120, v18, s[4:5] offset:2048
	global_load_dword v121, v18, s[4:5] offset:2112
	global_load_dword v122, v22, s[4:5] offset:2560
	global_load_dword v123, v22, s[4:5] offset:2816
	s_add_i32 s71, s70, 0x1000
	s_mul_i32 s71, s71, 0xc00
	s_add_u32 s71, s71, 0xb7c8000
	s_add_u32 s4, s54, s71
	s_addc_u32 s5, s55, 0
	global_load_dword v132, v18, s[4:5] offset:2048
	global_load_dword v133, v18, s[4:5] offset:2112
	global_load_dword v134, v22, s[4:5] offset:2560
	global_load_dword v135, v22, s[4:5] offset:2816
	s_add_i32 s71, s70, 0x1800
	s_mul_i32 s71, s71, 0xc00
	s_add_u32 s71, s71, 0xb7c8000
	s_add_u32 s4, s54, s71
	s_addc_u32 s5, s55, 0
	global_load_dword v144, v18, s[4:5] offset:2048
	global_load_dword v145, v18, s[4:5] offset:2112
	global_load_dword v146, v22, s[4:5] offset:2560
	global_load_dword v147, v22, s[4:5] offset:2816
	s_add_i32 s71, s70, 0x2000
	s_mul_i32 s71, s71, 0xc00
	s_add_u32 s71, s71, 0xb7c8000
	s_add_u32 s4, s54, s71
	s_addc_u32 s5, s55, 0
	global_load_dword v156, v18, s[4:5] offset:2048
	global_load_dword v157, v18, s[4:5] offset:2112
	global_load_dword v158, v22, s[4:5] offset:2560
	global_load_dword v159, v22, s[4:5] offset:2816
	s_add_i32 s71, s70, 0x2800
	s_mul_i32 s71, s71, 0xc00
	s_add_u32 s71, s71, 0xb7c8000
	s_add_u32 s4, s54, s71
	s_addc_u32 s5, s55, 0
	global_load_dword v168, v18, s[4:5] offset:2048
	global_load_dword v169, v18, s[4:5] offset:2112
	global_load_dword v170, v22, s[4:5] offset:2560
	global_load_dword v171, v22, s[4:5] offset:2816
	s_add_i32 s71, s70, 0x0
	s_lshr_b32 s11, s71, 8
	s_and_b32 s10, s71, 0xff
	s_lshl_b32 s11, s11, 9
	s_add_i32 s10, s10, s11
	s_lshl_b32 s74, s71, 11
	s_add_u32 s74, s74, 0x87c8000
	s_add_u32 s74, s54, s74
	s_addc_u32 s75, s55, 0
	s_lshl_b32 s76, s10, 8
	s_add_u32 s78, s76, 0x12bc8000
	s_add_u32 s76, s76, 0x129c8000
	s_add_u32 s76, s54, s76
	s_addc_u32 s77, s55, 0
	s_add_u32 s78, s54, s78
	s_addc_u32 s79, s55, 0
	s_add_u32 s80, s78, 0x10000
	s_addc_u32 s81, s79, 0
	s_waitcnt vmcnt(20)
	global_store_dword v22, v110, s[78:79]
	global_store_dword v22, v111, s[80:81]
	s_lshl_b32 s4, s10, 9
	s_add_u32 s44, s4, 0x3400000
	s_add_u32 s4, s4, 0x3000000
	s_add_u32 s4, s52, s4
	s_addc_u32 s5, s53, 0
	s_add_u32 s44, s52, s44
	s_addc_u32 s45, s53, 0
	s_add_u32 s46, s44, 0x20000
	s_addc_u32 s47, s45, 0
	v_lshlrev_b32_e32 v72, 16, v110
	v_and_b32_e32 v73, 0xffff0000, v110
	v_lshlrev_b32_e32 v74, 16, v111
	v_and_b32_e32 v75, 0xffff0000, v111
	global_store_dwordx2 v23, v[72:73], s[44:45]
	global_store_dwordx2 v23, v[74:75], s[46:47]
	v_lshlrev_b32_e32 v46, 16, v108
	v_and_b32_e32 v47, 0xffff0000, v108
	v_lshlrev_b32_e32 v48, 16, v109
	v_and_b32_e32 v49, 0xffff0000, v109
	v_mul_f32_e32 v54, v46, v46
	v_fmac_f32_e32 v54, v47, v47
	v_fmac_f32_e32 v54, v48, v48
	v_fmac_f32_e32 v54, v49, v49
	s_nop 1
	v_add_f32_dpp v54, v54, v54 quad_perm:[1,0,3,2] row_mask:0xf bank_mask:0xf
	s_nop 1
	v_add_f32_dpp v54, v54, v54 quad_perm:[2,3,0,1] row_mask:0xf bank_mask:0xf
	s_nop 1
	v_add_f32_dpp v54, v54, v54 row_half_mirror row_mask:0xf bank_mask:0xf
	s_nop 1
	v_add_f32_dpp v54, v54, v54 row_mirror row_mask:0xf bank_mask:0xf
	v_mov_b32_e32 v59, v54
	s_nop 1
	v_permlane16_swap_b32_e32 v54, v59
	v_add_f32_e32 v54, v54, v59
	v_fmamk_f32 v54, v54, 0x3c000000, v207
	v_rsq_f32_e32 v59, v54
	s_nop 0
	v_mul_f32_e32 v54, v54, v59
	v_fma_f32 v54, -v54, v59, 1.0
	v_mul_f32_e32 v54, 0.5, v54
	v_fmac_f32_e32 v59, v59, v54
	v_mul_f32_e32 v46, v46, v59
	v_mul_f32_e32 v47, v47, v59
	v_mul_f32_e32 v48, v48, v59
	v_mul_f32_e32 v49, v49, v59
	v_mul_f32_e32 v46, v46, v8
	v_mul_f32_e32 v47, v47, v9
	v_mul_f32_e32 v48, v48, v10
	v_mul_f32_e32 v49, v49, v11
	global_store_dwordx2 v21, v[46:47], s[4:5]
	global_store_dwordx2 v21, v[48:49], s[4:5] offset:128
	v_cvt_pk_bf16_f32 v68, v46, v47
	v_cvt_pk_bf16_f32 v69, v48, v49
	global_store_dword v20, v68, s[76:77]
	global_store_dword v20, v69, s[76:77] offset:64
	s_add_i32 s71, s70, 0x800
	s_lshr_b32 s11, s71, 8
	s_and_b32 s10, s71, 0xff
	s_lshl_b32 s11, s11, 9
	s_add_i32 s10, s10, s11
	s_lshl_b32 s74, s71, 11
	s_add_u32 s74, s74, 0x87c8000
	s_add_u32 s74, s54, s74
	s_addc_u32 s75, s55, 0
	s_lshl_b32 s76, s10, 8
	s_add_u32 s78, s76, 0x12bc8000
	s_add_u32 s76, s76, 0x129c8000
	s_add_u32 s76, s54, s76
	s_addc_u32 s77, s55, 0
	s_add_u32 s78, s54, s78
	s_addc_u32 s79, s55, 0
	s_add_u32 s80, s78, 0x10000
	s_addc_u32 s81, s79, 0
	s_waitcnt vmcnt(24)
	global_store_dword v22, v122, s[78:79]
	global_store_dword v22, v123, s[80:81]
	s_lshl_b32 s4, s10, 9
	s_add_u32 s44, s4, 0x3400000
	s_add_u32 s4, s4, 0x3000000
	s_add_u32 s4, s52, s4
	s_addc_u32 s5, s53, 0
	s_add_u32 s44, s52, s44
	s_addc_u32 s45, s53, 0
	s_add_u32 s46, s44, 0x20000
	s_addc_u32 s47, s45, 0
	v_lshlrev_b32_e32 v72, 16, v122
	v_and_b32_e32 v73, 0xffff0000, v122
	v_lshlrev_b32_e32 v74, 16, v123
	v_and_b32_e32 v75, 0xffff0000, v123
	global_store_dwordx2 v23, v[72:73], s[44:45]
	global_store_dwordx2 v23, v[74:75], s[46:47]
	v_lshlrev_b32_e32 v46, 16, v120
	v_and_b32_e32 v47, 0xffff0000, v120
	v_lshlrev_b32_e32 v48, 16, v121
	v_and_b32_e32 v49, 0xffff0000, v121
	v_mul_f32_e32 v54, v46, v46
	v_fmac_f32_e32 v54, v47, v47
	v_fmac_f32_e32 v54, v48, v48
	v_fmac_f32_e32 v54, v49, v49
	s_nop 1
	v_add_f32_dpp v54, v54, v54 quad_perm:[1,0,3,2] row_mask:0xf bank_mask:0xf
	s_nop 1
	v_add_f32_dpp v54, v54, v54 quad_perm:[2,3,0,1] row_mask:0xf bank_mask:0xf
	s_nop 1
	v_add_f32_dpp v54, v54, v54 row_half_mirror row_mask:0xf bank_mask:0xf
	s_nop 1
	v_add_f32_dpp v54, v54, v54 row_mirror row_mask:0xf bank_mask:0xf
	v_mov_b32_e32 v59, v54
	s_nop 1
	v_permlane16_swap_b32_e32 v54, v59
	v_add_f32_e32 v54, v54, v59
	v_fmamk_f32 v54, v54, 0x3c000000, v207
	v_rsq_f32_e32 v59, v54
	s_nop 0
	v_mul_f32_e32 v54, v54, v59
	v_fma_f32 v54, -v54, v59, 1.0
	v_mul_f32_e32 v54, 0.5, v54
	v_fmac_f32_e32 v59, v59, v54
	v_mul_f32_e32 v46, v46, v59
	v_mul_f32_e32 v47, v47, v59
	v_mul_f32_e32 v48, v48, v59
	v_mul_f32_e32 v49, v49, v59
	v_mul_f32_e32 v46, v46, v8
	v_mul_f32_e32 v47, v47, v9
	v_mul_f32_e32 v48, v48, v10
	v_mul_f32_e32 v49, v49, v11
	global_store_dwordx2 v21, v[46:47], s[4:5]
	global_store_dwordx2 v21, v[48:49], s[4:5] offset:128
	v_cvt_pk_bf16_f32 v68, v46, v47
	v_cvt_pk_bf16_f32 v69, v48, v49
	global_store_dword v20, v68, s[76:77]
	global_store_dword v20, v69, s[76:77] offset:64
	s_add_i32 s71, s70, 0x1000
	s_bfe_u32 s40, s71, 0x60006
	s_and_b32 s41, s71, 63
	s_sub_i32 s10, s71, 0x1000
	s_lshr_b32 s11, s10, 12
	s_and_b32 s10, s10, 0xfff
	s_mulk_i32 s11, 0x2200
	s_add_i32 s10, s10, s11
	s_addk_i32 s10, 0x100
	s_lshl_b32 s74, s71, 11
	s_add_u32 s74, s74, 0x87c8000
	s_add_u32 s74, s54, s74
	s_addc_u32 s75, s55, 0
	s_lshl_b32 s76, s10, 8
	s_add_u32 s78, s76, 0x13208000
	s_add_u32 s76, s76, 0x12dc8000
	s_add_u32 s76, s54, s76
	s_addc_u32 s77, s55, 0
	s_add_u32 s78, s54, s78
	s_addc_u32 s79, s55, 0
	s_add_u32 s80, s78, 0x110000
	s_addc_u32 s81, s79, 0
	s_waitcnt vmcnt(28)
	global_store_dword v22, v134, s[78:79]
	global_store_dword v22, v135, s[80:81]
	v_lshlrev_b32_e32 v46, 16, v132
	v_and_b32_e32 v47, 0xffff0000, v132
	v_lshlrev_b32_e32 v48, 16, v133
	v_and_b32_e32 v49, 0xffff0000, v133
	v_mul_f32_e32 v54, v46, v46
	v_fmac_f32_e32 v54, v47, v47
	v_fmac_f32_e32 v54, v48, v48
	v_fmac_f32_e32 v54, v49, v49
	s_nop 1
	v_add_f32_dpp v54, v54, v54 quad_perm:[1,0,3,2] row_mask:0xf bank_mask:0xf
	s_nop 1
	v_add_f32_dpp v54, v54, v54 quad_perm:[2,3,0,1] row_mask:0xf bank_mask:0xf
	s_nop 1
	v_add_f32_dpp v54, v54, v54 row_half_mirror row_mask:0xf bank_mask:0xf
	s_nop 1
	v_add_f32_dpp v54, v54, v54 row_mirror row_mask:0xf bank_mask:0xf
	v_mov_b32_e32 v59, v54
	s_nop 1
	v_permlane16_swap_b32_e32 v54, v59
	v_add_f32_e32 v54, v54, v59
	v_fmamk_f32 v54, v54, 0x3c000000, v207
	v_rsq_f32_e32 v59, v54
	s_nop 0
	v_mul_f32_e32 v54, v54, v59
	v_fma_f32 v54, -v54, v59, 1.0
	v_mul_f32_e32 v54, 0.5, v54
	v_fmac_f32_e32 v59, v59, v54
	v_mov_b32_e32 v70, s40
	v_mov_b32_e32 v71, s41
	v_cndmask_b32_e64 v70, v71, v70, s[42:43]
	v_cvt_f32_ubyte0_e32 v70, v70
	v_mul_f32_e32 v60, v26, v70
	v_mul_f32_e32 v62, v27, v70
	v_mul_f32_e32 v61, 0.15915494, v60
	v_mul_f32_e32 v63, 0.15915494, v62
	v_rndne_f32_e32 v61, v61
	v_rndne_f32_e32 v63, v63
	v_fmac_f32_e32 v60, 0xc0c90fdb, v61
	v_fmac_f32_e32 v62, 0xc0c90fdb, v63
	v_fmac_f32_e32 v60, 0x343bbd2e, v61
	v_fmac_f32_e32 v62, 0x343bbd2e, v63
	v_mul_f32_e32 v60, 0.15915494, v60
	v_mul_f32_e32 v62, 0.15915494, v62
	v_sin_f32_e32 v61, v60
	v_sin_f32_e32 v63, v62
	v_cos_f32_e32 v60, v60
	v_cos_f32_e32 v62, v62
	v_mul_f32_e32 v46, v46, v59
	v_mul_f32_e32 v47, v47, v59
	v_mul_f32_e32 v48, v48, v59
	v_mul_f32_e32 v49, v49, v59
	v_mul_f32_e32 v46, v46, v8
	v_mul_f32_e32 v47, v47, v9
	v_mul_f32_e32 v48, v48, v10
	v_mul_f32_e32 v49, v49, v11
	v_mul_f32_e32 v64, v61, v48
	v_mul_f32_e32 v65, v63, v49
	v_mul_f32_e32 v66, v60, v48
	v_mul_f32_e32 v67, v62, v49
	v_fma_f32 v64, v60, v46, -v64
	v_fma_f32 v65, v62, v47, -v65
	v_fmac_f32_e32 v66, v61, v46
	v_fmac_f32_e32 v67, v63, v47
	v_cvt_pk_bf16_f32 v68, v64, v65
	v_cvt_pk_bf16_f32 v69, v66, v67
	global_store_dword v19, v68, s[76:77]
	global_store_dword v19, v69, s[76:77] offset:64
	s_add_i32 s71, s70, 0x1800
	s_bfe_u32 s40, s71, 0x60006
	s_and_b32 s41, s71, 63
	s_sub_i32 s10, s71, 0x1000
	s_lshr_b32 s11, s10, 12
	s_and_b32 s10, s10, 0xfff
	s_mulk_i32 s11, 0x2200
	s_add_i32 s10, s10, s11
	s_addk_i32 s10, 0x100
	s_lshl_b32 s74, s71, 11
	s_add_u32 s74, s74, 0x87c8000
	s_add_u32 s74, s54, s74
	s_addc_u32 s75, s55, 0
	s_lshl_b32 s76, s10, 8
	s_add_u32 s78, s76, 0x13208000
	s_add_u32 s76, s76, 0x12dc8000
	s_add_u32 s76, s54, s76
	s_addc_u32 s77, s55, 0
	s_add_u32 s78, s54, s78
	s_addc_u32 s79, s55, 0
	s_add_u32 s80, s78, 0x110000
	s_addc_u32 s81, s79, 0
	s_waitcnt vmcnt(28)
	global_store_dword v22, v146, s[78:79]
	global_store_dword v22, v147, s[80:81]
	v_lshlrev_b32_e32 v46, 16, v144
	v_and_b32_e32 v47, 0xffff0000, v144
	v_lshlrev_b32_e32 v48, 16, v145
	v_and_b32_e32 v49, 0xffff0000, v145
	v_mul_f32_e32 v54, v46, v46
	v_fmac_f32_e32 v54, v47, v47
	v_fmac_f32_e32 v54, v48, v48
	v_fmac_f32_e32 v54, v49, v49
	s_nop 1
	v_add_f32_dpp v54, v54, v54 quad_perm:[1,0,3,2] row_mask:0xf bank_mask:0xf
	s_nop 1
	v_add_f32_dpp v54, v54, v54 quad_perm:[2,3,0,1] row_mask:0xf bank_mask:0xf
	s_nop 1
	v_add_f32_dpp v54, v54, v54 row_half_mirror row_mask:0xf bank_mask:0xf
	s_nop 1
	v_add_f32_dpp v54, v54, v54 row_mirror row_mask:0xf bank_mask:0xf
	v_mov_b32_e32 v59, v54
	s_nop 1
	v_permlane16_swap_b32_e32 v54, v59
	v_add_f32_e32 v54, v54, v59
	v_fmamk_f32 v54, v54, 0x3c000000, v207
	v_rsq_f32_e32 v59, v54
	s_nop 0
	v_mul_f32_e32 v54, v54, v59
	v_fma_f32 v54, -v54, v59, 1.0
	v_mul_f32_e32 v54, 0.5, v54
	v_fmac_f32_e32 v59, v59, v54
	v_mov_b32_e32 v70, s40
	v_mov_b32_e32 v71, s41
	v_cndmask_b32_e64 v70, v71, v70, s[42:43]
	v_cvt_f32_ubyte0_e32 v70, v70
	v_mul_f32_e32 v60, v26, v70
	v_mul_f32_e32 v62, v27, v70
	v_mul_f32_e32 v61, 0.15915494, v60
	v_mul_f32_e32 v63, 0.15915494, v62
	v_rndne_f32_e32 v61, v61
	v_rndne_f32_e32 v63, v63
	v_fmac_f32_e32 v60, 0xc0c90fdb, v61
	v_fmac_f32_e32 v62, 0xc0c90fdb, v63
	v_fmac_f32_e32 v60, 0x343bbd2e, v61
	v_fmac_f32_e32 v62, 0x343bbd2e, v63
	v_mul_f32_e32 v60, 0.15915494, v60
	v_mul_f32_e32 v62, 0.15915494, v62
	v_sin_f32_e32 v61, v60
	v_sin_f32_e32 v63, v62
	v_cos_f32_e32 v60, v60
	v_cos_f32_e32 v62, v62
	v_mul_f32_e32 v46, v46, v59
	v_mul_f32_e32 v47, v47, v59
	v_mul_f32_e32 v48, v48, v59
	v_mul_f32_e32 v49, v49, v59
	v_mul_f32_e32 v46, v46, v8
	v_mul_f32_e32 v47, v47, v9
	v_mul_f32_e32 v48, v48, v10
	v_mul_f32_e32 v49, v49, v11
	v_mul_f32_e32 v64, v61, v48
	v_mul_f32_e32 v65, v63, v49
	v_mul_f32_e32 v66, v60, v48
	v_mul_f32_e32 v67, v62, v49
	v_fma_f32 v64, v60, v46, -v64
	v_fma_f32 v65, v62, v47, -v65
	v_fmac_f32_e32 v66, v61, v46
	v_fmac_f32_e32 v67, v63, v47
	v_cvt_pk_bf16_f32 v68, v64, v65
	v_cvt_pk_bf16_f32 v69, v66, v67
	global_store_dword v19, v68, s[76:77]
	global_store_dword v19, v69, s[76:77] offset:64
	s_add_i32 s71, s70, 0x2000
	s_bfe_u32 s40, s71, 0x60006
	s_and_b32 s41, s71, 63
	s_sub_i32 s10, s71, 0x1000
	s_lshr_b32 s11, s10, 12
	s_and_b32 s10, s10, 0xfff
	s_mulk_i32 s11, 0x2200
	s_add_i32 s10, s10, s11
	s_addk_i32 s10, 0x100
	s_lshl_b32 s74, s71, 11
	s_add_u32 s74, s74, 0x87c8000
	s_add_u32 s74, s54, s74
	s_addc_u32 s75, s55, 0
	s_lshl_b32 s76, s10, 8
	s_add_u32 s78, s76, 0x13208000
	s_add_u32 s76, s76, 0x12dc8000
	s_add_u32 s76, s54, s76
	s_addc_u32 s77, s55, 0
	s_add_u32 s78, s54, s78
	s_addc_u32 s79, s55, 0
	s_add_u32 s80, s78, 0x110000
	s_addc_u32 s81, s79, 0
	s_waitcnt vmcnt(28)
	global_store_dword v22, v158, s[78:79]
	global_store_dword v22, v159, s[80:81]
	v_lshlrev_b32_e32 v46, 16, v156
	v_and_b32_e32 v47, 0xffff0000, v156
	v_lshlrev_b32_e32 v48, 16, v157
	v_and_b32_e32 v49, 0xffff0000, v157
	v_mul_f32_e32 v54, v46, v46
	v_fmac_f32_e32 v54, v47, v47
	v_fmac_f32_e32 v54, v48, v48
	v_fmac_f32_e32 v54, v49, v49
	s_nop 1
	v_add_f32_dpp v54, v54, v54 quad_perm:[1,0,3,2] row_mask:0xf bank_mask:0xf
	s_nop 1
	v_add_f32_dpp v54, v54, v54 quad_perm:[2,3,0,1] row_mask:0xf bank_mask:0xf
	s_nop 1
	v_add_f32_dpp v54, v54, v54 row_half_mirror row_mask:0xf bank_mask:0xf
	s_nop 1
	v_add_f32_dpp v54, v54, v54 row_mirror row_mask:0xf bank_mask:0xf
	v_mov_b32_e32 v59, v54
	s_nop 1
	v_permlane16_swap_b32_e32 v54, v59
	v_add_f32_e32 v54, v54, v59
	v_fmamk_f32 v54, v54, 0x3c000000, v207
	v_rsq_f32_e32 v59, v54
	s_nop 0
	v_mul_f32_e32 v54, v54, v59
	v_fma_f32 v54, -v54, v59, 1.0
	v_mul_f32_e32 v54, 0.5, v54
	v_fmac_f32_e32 v59, v59, v54
	v_mov_b32_e32 v70, s40
	v_mov_b32_e32 v71, s41
	v_cndmask_b32_e64 v70, v71, v70, s[42:43]
	v_cvt_f32_ubyte0_e32 v70, v70
	v_mul_f32_e32 v60, v26, v70
	v_mul_f32_e32 v62, v27, v70
	v_mul_f32_e32 v61, 0.15915494, v60
	v_mul_f32_e32 v63, 0.15915494, v62
	v_rndne_f32_e32 v61, v61
	v_rndne_f32_e32 v63, v63
	v_fmac_f32_e32 v60, 0xc0c90fdb, v61
	v_fmac_f32_e32 v62, 0xc0c90fdb, v63
	v_fmac_f32_e32 v60, 0x343bbd2e, v61
	v_fmac_f32_e32 v62, 0x343bbd2e, v63
	v_mul_f32_e32 v60, 0.15915494, v60
	v_mul_f32_e32 v62, 0.15915494, v62
	v_sin_f32_e32 v61, v60
	v_sin_f32_e32 v63, v62
	v_cos_f32_e32 v60, v60
	v_cos_f32_e32 v62, v62
	v_mul_f32_e32 v46, v46, v59
	v_mul_f32_e32 v47, v47, v59
	v_mul_f32_e32 v48, v48, v59
	v_mul_f32_e32 v49, v49, v59
	v_mul_f32_e32 v46, v46, v8
	v_mul_f32_e32 v47, v47, v9
	v_mul_f32_e32 v48, v48, v10
	v_mul_f32_e32 v49, v49, v11
	v_mul_f32_e32 v64, v61, v48
	v_mul_f32_e32 v65, v63, v49
	v_mul_f32_e32 v66, v60, v48
	v_mul_f32_e32 v67, v62, v49
	v_fma_f32 v64, v60, v46, -v64
	v_fma_f32 v65, v62, v47, -v65
	v_fmac_f32_e32 v66, v61, v46
	v_fmac_f32_e32 v67, v63, v47
	v_cvt_pk_bf16_f32 v68, v64, v65
	v_cvt_pk_bf16_f32 v69, v66, v67
	global_store_dword v19, v68, s[76:77]
	global_store_dword v19, v69, s[76:77] offset:64
	s_add_i32 s71, s70, 0x2800
	s_bfe_u32 s40, s71, 0x60006
	s_and_b32 s41, s71, 63
	s_sub_i32 s10, s71, 0x1000
	s_lshr_b32 s11, s10, 12
	s_and_b32 s10, s10, 0xfff
	s_mulk_i32 s11, 0x2200
	s_add_i32 s10, s10, s11
	s_addk_i32 s10, 0x100
	s_lshl_b32 s74, s71, 11
	s_add_u32 s74, s74, 0x87c8000
	s_add_u32 s74, s54, s74
	s_addc_u32 s75, s55, 0
	s_lshl_b32 s76, s10, 8
	s_add_u32 s78, s76, 0x13208000
	s_add_u32 s76, s76, 0x12dc8000
	s_add_u32 s76, s54, s76
	s_addc_u32 s77, s55, 0
	s_add_u32 s78, s54, s78
	s_addc_u32 s79, s55, 0
	s_add_u32 s80, s78, 0x110000
	s_addc_u32 s81, s79, 0
	s_waitcnt vmcnt(28)
	global_store_dword v22, v170, s[78:79]
	global_store_dword v22, v171, s[80:81]
	v_lshlrev_b32_e32 v46, 16, v168
	v_and_b32_e32 v47, 0xffff0000, v168
	v_lshlrev_b32_e32 v48, 16, v169
	v_and_b32_e32 v49, 0xffff0000, v169
	v_mul_f32_e32 v54, v46, v46
	v_fmac_f32_e32 v54, v47, v47
	v_fmac_f32_e32 v54, v48, v48
	v_fmac_f32_e32 v54, v49, v49
	s_nop 1
	v_add_f32_dpp v54, v54, v54 quad_perm:[1,0,3,2] row_mask:0xf bank_mask:0xf
	s_nop 1
	v_add_f32_dpp v54, v54, v54 quad_perm:[2,3,0,1] row_mask:0xf bank_mask:0xf
	s_nop 1
	v_add_f32_dpp v54, v54, v54 row_half_mirror row_mask:0xf bank_mask:0xf
	s_nop 1
	v_add_f32_dpp v54, v54, v54 row_mirror row_mask:0xf bank_mask:0xf
	v_mov_b32_e32 v59, v54
	s_nop 1
	v_permlane16_swap_b32_e32 v54, v59
	v_add_f32_e32 v54, v54, v59
	v_fmamk_f32 v54, v54, 0x3c000000, v207
	v_rsq_f32_e32 v59, v54
	s_nop 0
	v_mul_f32_e32 v54, v54, v59
	v_fma_f32 v54, -v54, v59, 1.0
	v_mul_f32_e32 v54, 0.5, v54
	v_fmac_f32_e32 v59, v59, v54
	v_mov_b32_e32 v70, s40
	v_mov_b32_e32 v71, s41
	v_cndmask_b32_e64 v70, v71, v70, s[42:43]
	v_cvt_f32_ubyte0_e32 v70, v70
	v_mul_f32_e32 v60, v26, v70
	v_mul_f32_e32 v62, v27, v70
	v_mul_f32_e32 v61, 0.15915494, v60
	v_mul_f32_e32 v63, 0.15915494, v62
	v_rndne_f32_e32 v61, v61
	v_rndne_f32_e32 v63, v63
	v_fmac_f32_e32 v60, 0xc0c90fdb, v61
	v_fmac_f32_e32 v62, 0xc0c90fdb, v63
	v_fmac_f32_e32 v60, 0x343bbd2e, v61
	v_fmac_f32_e32 v62, 0x343bbd2e, v63
	v_mul_f32_e32 v60, 0.15915494, v60
	v_mul_f32_e32 v62, 0.15915494, v62
	v_sin_f32_e32 v61, v60
	v_sin_f32_e32 v63, v62
	v_cos_f32_e32 v60, v60
	v_cos_f32_e32 v62, v62
	v_mul_f32_e32 v46, v46, v59
	v_mul_f32_e32 v47, v47, v59
	v_mul_f32_e32 v48, v48, v59
	v_mul_f32_e32 v49, v49, v59
	v_mul_f32_e32 v46, v46, v8
	v_mul_f32_e32 v47, v47, v9
	v_mul_f32_e32 v48, v48, v10
	v_mul_f32_e32 v49, v49, v11
	v_mul_f32_e32 v64, v61, v48
	v_mul_f32_e32 v65, v63, v49
	v_mul_f32_e32 v66, v60, v48
	v_mul_f32_e32 v67, v62, v49
	v_fma_f32 v64, v60, v46, -v64
	v_fma_f32 v65, v62, v47, -v65
	v_fmac_f32_e32 v66, v61, v46
	v_fmac_f32_e32 v67, v63, v47
	v_cvt_pk_bf16_f32 v68, v64, v65
	v_cvt_pk_bf16_f32 v69, v66, v67
	global_store_dword v19, v68, s[76:77]
	global_store_dword v19, v69, s[76:77] offset:64

.LBB0_891:
	s_cmpk_gt_i32 s67, 0xff
	s_mov_b64 s[40:41], -1
	s_cbranch_scc0 .LBB0_896
	s_add_i32 s2, s67, 0xffffff00
	s_lshr_b32 s72, s2, 3
	s_and_b32 s2, s67, 7
	s_mul_i32 s4, s72, 0xc0000
	s_add_u32 s4, s4, 0x3000000
	s_add_u32 s3, s39, s4
	s_addc_u32 s4, s52, 0
	s_lshl_b32 s5, s2, 8
	s_add_u32 s40, s3, s5
	s_addc_u32 s41, s4, 0
	s_lshl_b32 s3, s67, 14
	s_and_b32 s3, s3, 0x10000
	s_lshl_b64 s[4:5], s[72:73], 17
	s_waitcnt vmcnt(2)
	v_mov_b32_e32 v58, v204
	s_or_b32 s3, s4, s3
	s_add_u32 s44, s53, s3
	v_ashrrev_i32_e32 v16, 4, v58
	v_lshlrev_b32_e32 v22, 3, v58
	v_add_u32_e32 v18, 32, v16
	s_addc_u32 s45, s54, s5
	s_waitcnt vmcnt(0)
	v_and_b32_e32 v0, 0x78, v22
	v_ashrrev_i32_e32 v17, 31, v16
	v_ashrrev_i32_e32 v19, 31, v18
	s_add_u32 s48, s55, s3
	v_lshlrev_b32_e32 v23, 1, v0
	s_waitcnt vmcnt(0)
	v_lshlrev_b64 v[32:33], 8, v[16:17]
	v_lshlrev_b64 v[8:9], 8, v[18:19]
	s_addc_u32 s49, s60, s5
	v_or_b32_e32 v32, v32, v23
	v_or_b32_e32 v8, v8, v23
	v_lshl_add_u64 v[0:1], s[48:49], 0, v[32:33]
	v_lshl_add_u64 v[4:5], s[48:49], 0, v[8:9]
	v_lshl_add_u64 v[10:11], s[44:45], 0, v[32:33]
	v_lshl_add_u64 v[12:13], s[44:45], 0, v[8:9]
	global_load_dwordx4 v[0:3], v[0:1], off
	s_nop 0
	global_load_dwordx4 v[4:7], v[4:5], off
	s_nop 0
	global_load_dwordx4 v[8:11], v[10:11], off
	s_nop 0
	global_load_dwordx4 v[12:15], v[12:13], off
	v_ashrrev_i32_e32 v186, 1, v58
	s_movk_i32 s3, 0xffe0
	v_bfi_b32 v20, s3, v186, v58
	v_ashrrev_i32_e32 v21, 31, v20
	v_bfe_u32 v162, v58, 5, 1
	v_mul_u32_u24_e32 v20, 0xc00, v20
	v_lshl_add_u64 v[20:21], s[40:41], 0, v[20:21]
	v_lshlrev_b32_e32 v96, 4, v162
	v_lshl_add_u64 v[20:21], v[20:21], 0, v[96:97]
	global_load_dwordx4 v[114:117], v[20:21], off
	global_load_dwordx4 v[110:113], v[20:21], off offset:32
	global_load_dwordx4 v[122:125], v[20:21], off offset:64
	global_load_dwordx4 v[126:129], v[20:21], off offset:96
	global_load_dwordx4 v[118:121], v[20:21], off offset:128
	global_load_dwordx4 v[106:109], v[20:21], off offset:160
	global_load_dwordx4 v[102:105], v[20:21], off offset:192
	global_load_dwordx4 v[98:101], v[20:21], off offset:224
	v_and_b32_e32 v19, 0xfffff0, v16
	v_lshlrev_b32_e32 v24, 1, v16
	v_lshrrev_b32_e32 v25, 1, v16
	v_and_b32_e32 v26, 3, v16
	v_and_or_b32 v19, v24, 8, v19
	v_and_or_b32 v24, v25, 4, v26
	v_and_b32_e32 v25, 0xfffff0, v18
	v_lshlrev_b32_e32 v26, 1, v18
	v_and_b32_e32 v17, 0x70, v58
	v_bfe_u32 v22, v22, 5, 2
	v_lshlrev_b32_e32 v16, 8, v16
	v_lshlrev_b32_e32 v18, 8, v18
	v_lshrrev_b32_e32 v19, 1, v19
	v_and_or_b32 v25, v26, 8, v25
	v_bitop3_b32 v16, v23, v16, v17 bitop3:0xde
	v_bitop3_b32 v17, v23, v18, v17 bitop3:0xde
	v_or_b32_e32 v18, v19, v22
	v_lshrrev_b32_e32 v19, 1, v25
	v_lshlrev_b32_e32 v24, 6, v24
	v_and_b32_e32 v27, 48, v23
	v_add_u32_e32 v182, 0, v16
	v_add_u32_e32 v183, 0, v17
	v_lshlrev_b32_e32 v16, 9, v18
	v_or_b32_e32 v17, v19, v22
	v_and_b32_e32 v163, 31, v58
	v_lshlrev_b32_e32 v59, 4, v58
	v_or3_b32 v16, v16, v24, v27
	v_lshlrev_b32_e32 v17, 9, v17
	v_lshlrev_b32_e32 v54, 8, v163
	v_and_b32_e32 v55, 0x70, v59
	v_or3_b32 v17, v17, v24, v27
	v_add_u32_e32 v184, 0, v16
	v_add_u32_e32 v185, 0, v17
	s_waitcnt vmcnt(0)
	v_or_b32_e32 v20, 32, v96
	v_bitop3_b32 v20, v20, v54, v55 bitop3:0xde
	v_add_u32_e32 v176, 0, v20
	s_mov_b64 s[4:5], 0x4000
	v_lshl_add_u64 v[42:43], v[32:33], 0, s[4:5]
	s_mov_b64 s[4:5], 0x6000
	v_or_b32_e32 v56, 0xe0, v96
	v_lshl_add_u64 v[44:45], v[32:33], 0, s[4:5]
	v_lshl_add_u64 v[50:51], s[44:45], 0, v[42:43]
	v_lshl_add_u64 v[52:53], s[44:45], 0, v[44:45]
	v_lshl_add_u64 v[42:43], s[48:49], 0, v[42:43]
	v_lshl_add_u64 v[46:47], s[48:49], 0, v[44:45]
	s_waitcnt vmcnt(11)
	ds_write_b128 v184, v[0:3]
	s_waitcnt vmcnt(10)
	ds_write_b128 v185, v[4:7]
	s_waitcnt vmcnt(9)
	ds_write_b128 v182, v[8:11] offset:32768
	s_waitcnt vmcnt(8)
	ds_write_b128 v183, v[12:15] offset:32768
	s_load_dwordx2 s[100:101], s[88:89], 0x80
	v_lshlrev_b32_e32 v175, 5, v162
	s_waitcnt lgkmcnt(0)
	global_load_dwordx4 v[130:133], v175, s[100:101] offset:0
	global_load_dwordx4 v[134:137], v175, s[100:101] offset:16
	global_load_dwordx4 v[138:141], v175, s[100:101] offset:64
	global_load_dwordx4 v[142:145], v175, s[100:101] offset:80
	global_load_dwordx4 v[146:149], v175, s[100:101] offset:128
	global_load_dwordx4 v[150:153], v175, s[100:101] offset:144
	global_load_dwordx4 v[154:157], v175, s[100:101] offset:192
	global_load_dwordx4 v[158:161], v175, s[100:101] offset:208
	global_load_dwordx4 v[224:227], v175, s[100:101] offset:256
	global_load_dwordx4 v[228:231], v175, s[100:101] offset:272
	global_load_dwordx4 v[232:235], v175, s[100:101] offset:320
	global_load_dwordx4 v[236:239], v175, s[100:101] offset:336
	global_load_dwordx4 v[240:243], v175, s[100:101] offset:384
	global_load_dwordx4 v[244:247], v175, s[100:101] offset:400
	global_load_dwordx4 v[248:251], v175, s[100:101] offset:448
	global_load_dwordx4 v[164:167], v175, s[100:101] offset:464
	v_lshlrev_b32_e32 v24, 16, v114
	v_and_b32_e32 v25, 0xffff0000, v114
	v_lshlrev_b32_e32 v26, 16, v115
	v_and_b32_e32 v27, 0xffff0000, v115
	v_lshlrev_b32_e32 v28, 16, v116
	v_and_b32_e32 v29, 0xffff0000, v116
	v_lshlrev_b32_e32 v30, 16, v117
	v_and_b32_e32 v31, 0xffff0000, v117
	v_mul_f32_e32 v168, v24, v24
	v_fmac_f32_e32 v168, v25, v25
	v_fmac_f32_e32 v168, v26, v26
	v_fmac_f32_e32 v168, v27, v27
	v_fmac_f32_e32 v168, v28, v28
	v_fmac_f32_e32 v168, v29, v29
	v_fmac_f32_e32 v168, v30, v30
	v_fmac_f32_e32 v168, v31, v31
	v_lshlrev_b32_e32 v24, 16, v110
	v_and_b32_e32 v25, 0xffff0000, v110
	v_lshlrev_b32_e32 v26, 16, v111
	v_and_b32_e32 v27, 0xffff0000, v111
	v_lshlrev_b32_e32 v28, 16, v112
	v_and_b32_e32 v29, 0xffff0000, v112
	v_lshlrev_b32_e32 v30, 16, v113
	v_and_b32_e32 v31, 0xffff0000, v113
	v_fmac_f32_e32 v168, v24, v24
	v_fmac_f32_e32 v168, v25, v25
	v_fmac_f32_e32 v168, v26, v26
	v_fmac_f32_e32 v168, v27, v27
	v_fmac_f32_e32 v168, v28, v28
	v_fmac_f32_e32 v168, v29, v29
	v_fmac_f32_e32 v168, v30, v30
	v_fmac_f32_e32 v168, v31, v31
	v_lshlrev_b32_e32 v24, 16, v122
	v_and_b32_e32 v25, 0xffff0000, v122
	v_lshlrev_b32_e32 v26, 16, v123
	v_and_b32_e32 v27, 0xffff0000, v123
	v_lshlrev_b32_e32 v28, 16, v124
	v_and_b32_e32 v29, 0xffff0000, v124
	v_lshlrev_b32_e32 v30, 16, v125
	v_and_b32_e32 v31, 0xffff0000, v125
	v_fmac_f32_e32 v168, v24, v24
	v_fmac_f32_e32 v168, v25, v25
	v_fmac_f32_e32 v168, v26, v26
	v_fmac_f32_e32 v168, v27, v27
	v_fmac_f32_e32 v168, v28, v28
	v_fmac_f32_e32 v168, v29, v29
	v_fmac_f32_e32 v168, v30, v30
	v_fmac_f32_e32 v168, v31, v31
	v_lshlrev_b32_e32 v24, 16, v126
	v_and_b32_e32 v25, 0xffff0000, v126
	v_lshlrev_b32_e32 v26, 16, v127
	v_and_b32_e32 v27, 0xffff0000, v127
	v_lshlrev_b32_e32 v28, 16, v128
	v_and_b32_e32 v29, 0xffff0000, v128
	v_lshlrev_b32_e32 v30, 16, v129
	v_and_b32_e32 v31, 0xffff0000, v129
	v_fmac_f32_e32 v168, v24, v24
	v_fmac_f32_e32 v168, v25, v25
	v_fmac_f32_e32 v168, v26, v26
	v_fmac_f32_e32 v168, v27, v27
	v_fmac_f32_e32 v168, v28, v28
	v_fmac_f32_e32 v168, v29, v29
	v_fmac_f32_e32 v168, v30, v30
	v_fmac_f32_e32 v168, v31, v31
	v_lshlrev_b32_e32 v24, 16, v118
	v_and_b32_e32 v25, 0xffff0000, v118
	v_lshlrev_b32_e32 v26, 16, v119
	v_and_b32_e32 v27, 0xffff0000, v119
	v_lshlrev_b32_e32 v28, 16, v120
	v_and_b32_e32 v29, 0xffff0000, v120
	v_lshlrev_b32_e32 v30, 16, v121
	v_and_b32_e32 v31, 0xffff0000, v121
	v_fmac_f32_e32 v168, v24, v24
	v_fmac_f32_e32 v168, v25, v25
	v_fmac_f32_e32 v168, v26, v26
	v_fmac_f32_e32 v168, v27, v27
	v_fmac_f32_e32 v168, v28, v28
	v_fmac_f32_e32 v168, v29, v29
	v_fmac_f32_e32 v168, v30, v30
	v_fmac_f32_e32 v168, v31, v31
	v_lshlrev_b32_e32 v24, 16, v106
	v_and_b32_e32 v25, 0xffff0000, v106
	v_lshlrev_b32_e32 v26, 16, v107
	v_and_b32_e32 v27, 0xffff0000, v107
	v_lshlrev_b32_e32 v28, 16, v108
	v_and_b32_e32 v29, 0xffff0000, v108
	v_lshlrev_b32_e32 v30, 16, v109
	v_and_b32_e32 v31, 0xffff0000, v109
	v_fmac_f32_e32 v168, v24, v24
	v_fmac_f32_e32 v168, v25, v25
	v_fmac_f32_e32 v168, v26, v26
	v_fmac_f32_e32 v168, v27, v27
	v_fmac_f32_e32 v168, v28, v28
	v_fmac_f32_e32 v168, v29, v29
	v_fmac_f32_e32 v168, v30, v30
	v_fmac_f32_e32 v168, v31, v31
	v_lshlrev_b32_e32 v24, 16, v102
	v_and_b32_e32 v25, 0xffff0000, v102
	v_lshlrev_b32_e32 v26, 16, v103
	v_and_b32_e32 v27, 0xffff0000, v103
	v_lshlrev_b32_e32 v28, 16, v104
	v_and_b32_e32 v29, 0xffff0000, v104
	v_lshlrev_b32_e32 v30, 16, v105
	v_and_b32_e32 v31, 0xffff0000, v105
	v_fmac_f32_e32 v168, v24, v24
	v_fmac_f32_e32 v168, v25, v25
	v_fmac_f32_e32 v168, v26, v26
	v_fmac_f32_e32 v168, v27, v27
	v_fmac_f32_e32 v168, v28, v28
	v_fmac_f32_e32 v168, v29, v29
	v_fmac_f32_e32 v168, v30, v30
	v_fmac_f32_e32 v168, v31, v31
	v_lshlrev_b32_e32 v24, 16, v98
	v_and_b32_e32 v25, 0xffff0000, v98
	v_lshlrev_b32_e32 v26, 16, v99
	v_and_b32_e32 v27, 0xffff0000, v99
	v_lshlrev_b32_e32 v28, 16, v100
	v_and_b32_e32 v29, 0xffff0000, v100
	v_lshlrev_b32_e32 v30, 16, v101
	v_and_b32_e32 v31, 0xffff0000, v101
	v_fmac_f32_e32 v168, v24, v24
	v_fmac_f32_e32 v168, v25, v25
	v_fmac_f32_e32 v168, v26, v26
	v_fmac_f32_e32 v168, v27, v27
	v_fmac_f32_e32 v168, v28, v28
	v_fmac_f32_e32 v168, v29, v29
	v_fmac_f32_e32 v168, v30, v30
	v_fmac_f32_e32 v168, v31, v31
	v_mov_b32_e32 v170, v168
	s_nop 1
	v_permlane32_swap_b32_e32 v168, v170
	v_add_f32_e32 v168, v168, v170
	v_fmamk_f32 v168, v168, 0x3c000000, v207
	v_rsq_f32_e32 v169, v168
	s_nop 0
	v_mul_f32_e32 v170, v168, v169
	v_fma_f32 v170, -v170, v169, 1.0
	v_mul_f32_e32 v170, 0.5, v170
	v_fmac_f32_e32 v169, v169, v170
	s_waitcnt vmcnt(0)
	v_lshlrev_b32_e32 v24, 16, v114
	v_and_b32_e32 v25, 0xffff0000, v114
	v_lshlrev_b32_e32 v26, 16, v115
	v_and_b32_e32 v27, 0xffff0000, v115
	v_lshlrev_b32_e32 v28, 16, v116
	v_and_b32_e32 v29, 0xffff0000, v116
	v_lshlrev_b32_e32 v30, 16, v117
	v_and_b32_e32 v31, 0xffff0000, v117
	v_mul_f32_e32 v24, v24, v169
	v_mul_f32_e32 v25, v25, v169
	v_mul_f32_e32 v26, v26, v169
	v_mul_f32_e32 v27, v27, v169
	v_mul_f32_e32 v28, v28, v169
	v_mul_f32_e32 v29, v29, v169
	v_mul_f32_e32 v30, v30, v169
	v_mul_f32_e32 v31, v31, v169
	v_mul_f32_e32 v24, v24, v130
	v_mul_f32_e32 v25, v25, v131
	v_mul_f32_e32 v26, v26, v132
	v_mul_f32_e32 v27, v27, v133
	v_mul_f32_e32 v28, v28, v134
	v_mul_f32_e32 v29, v29, v135
	v_mul_f32_e32 v30, v30, v136
	v_mul_f32_e32 v31, v31, v137
	v_cvt_pk_bf16_f32 v114, v24, v25
	v_cvt_pk_bf16_f32 v115, v26, v27
	v_cvt_pk_bf16_f32 v116, v28, v29
	v_cvt_pk_bf16_f32 v117, v30, v31
	v_lshlrev_b32_e32 v24, 16, v110
	v_and_b32_e32 v25, 0xffff0000, v110
	v_lshlrev_b32_e32 v26, 16, v111
	v_and_b32_e32 v27, 0xffff0000, v111
	v_lshlrev_b32_e32 v28, 16, v112
	v_and_b32_e32 v29, 0xffff0000, v112
	v_lshlrev_b32_e32 v30, 16, v113
	v_and_b32_e32 v31, 0xffff0000, v113
	v_mul_f32_e32 v24, v24, v169
	v_mul_f32_e32 v25, v25, v169
	v_mul_f32_e32 v26, v26, v169
	v_mul_f32_e32 v27, v27, v169
	v_mul_f32_e32 v28, v28, v169
	v_mul_f32_e32 v29, v29, v169
	v_mul_f32_e32 v30, v30, v169
	v_mul_f32_e32 v31, v31, v169
	v_mul_f32_e32 v24, v24, v138
	v_mul_f32_e32 v25, v25, v139
	v_mul_f32_e32 v26, v26, v140
	v_mul_f32_e32 v27, v27, v141
	v_mul_f32_e32 v28, v28, v142
	v_mul_f32_e32 v29, v29, v143
	v_mul_f32_e32 v30, v30, v144
	v_mul_f32_e32 v31, v31, v145
	v_cvt_pk_bf16_f32 v110, v24, v25
	v_cvt_pk_bf16_f32 v111, v26, v27
	v_cvt_pk_bf16_f32 v112, v28, v29
	v_cvt_pk_bf16_f32 v113, v30, v31
	v_lshlrev_b32_e32 v24, 16, v122
	v_and_b32_e32 v25, 0xffff0000, v122
	v_lshlrev_b32_e32 v26, 16, v123
	v_and_b32_e32 v27, 0xffff0000, v123
	v_lshlrev_b32_e32 v28, 16, v124
	v_and_b32_e32 v29, 0xffff0000, v124
	v_lshlrev_b32_e32 v30, 16, v125
	v_and_b32_e32 v31, 0xffff0000, v125
	v_mul_f32_e32 v24, v24, v169
	v_mul_f32_e32 v25, v25, v169
	v_mul_f32_e32 v26, v26, v169
	v_mul_f32_e32 v27, v27, v169
	v_mul_f32_e32 v28, v28, v169
	v_mul_f32_e32 v29, v29, v169
	v_mul_f32_e32 v30, v30, v169
	v_mul_f32_e32 v31, v31, v169
	v_mul_f32_e32 v24, v24, v146
	v_mul_f32_e32 v25, v25, v147
	v_mul_f32_e32 v26, v26, v148
	v_mul_f32_e32 v27, v27, v149
	v_mul_f32_e32 v28, v28, v150
	v_mul_f32_e32 v29, v29, v151
	v_mul_f32_e32 v30, v30, v152
	v_mul_f32_e32 v31, v31, v153
	v_cvt_pk_bf16_f32 v122, v24, v25
	v_cvt_pk_bf16_f32 v123, v26, v27
	v_cvt_pk_bf16_f32 v124, v28, v29
	v_cvt_pk_bf16_f32 v125, v30, v31
	v_lshlrev_b32_e32 v24, 16, v126
	v_and_b32_e32 v25, 0xffff0000, v126
	v_lshlrev_b32_e32 v26, 16, v127
	v_and_b32_e32 v27, 0xffff0000, v127
	v_lshlrev_b32_e32 v28, 16, v128
	v_and_b32_e32 v29, 0xffff0000, v128
	v_lshlrev_b32_e32 v30, 16, v129
	v_and_b32_e32 v31, 0xffff0000, v129
	v_mul_f32_e32 v24, v24, v169
	v_mul_f32_e32 v25, v25, v169
	v_mul_f32_e32 v26, v26, v169
	v_mul_f32_e32 v27, v27, v169
	v_mul_f32_e32 v28, v28, v169
	v_mul_f32_e32 v29, v29, v169
	v_mul_f32_e32 v30, v30, v169
	v_mul_f32_e32 v31, v31, v169
	v_mul_f32_e32 v24, v24, v154
	v_mul_f32_e32 v25, v25, v155
	v_mul_f32_e32 v26, v26, v156
	v_mul_f32_e32 v27, v27, v157
	v_mul_f32_e32 v28, v28, v158
	v_mul_f32_e32 v29, v29, v159
	v_mul_f32_e32 v30, v30, v160
	v_mul_f32_e32 v31, v31, v161
	v_cvt_pk_bf16_f32 v126, v24, v25
	v_cvt_pk_bf16_f32 v127, v26, v27
	v_cvt_pk_bf16_f32 v128, v28, v29
	v_cvt_pk_bf16_f32 v129, v30, v31
	v_lshlrev_b32_e32 v24, 16, v118
	v_and_b32_e32 v25, 0xffff0000, v118
	v_lshlrev_b32_e32 v26, 16, v119
	v_and_b32_e32 v27, 0xffff0000, v119
	v_lshlrev_b32_e32 v28, 16, v120
	v_and_b32_e32 v29, 0xffff0000, v120
	v_lshlrev_b32_e32 v30, 16, v121
	v_and_b32_e32 v31, 0xffff0000, v121
	v_mul_f32_e32 v24, v24, v169
	v_mul_f32_e32 v25, v25, v169
	v_mul_f32_e32 v26, v26, v169
	v_mul_f32_e32 v27, v27, v169
	v_mul_f32_e32 v28, v28, v169
	v_mul_f32_e32 v29, v29, v169
	v_mul_f32_e32 v30, v30, v169
	v_mul_f32_e32 v31, v31, v169
	v_mul_f32_e32 v24, v24, v224
	v_mul_f32_e32 v25, v25, v225
	v_mul_f32_e32 v26, v26, v226
	v_mul_f32_e32 v27, v27, v227
	v_mul_f32_e32 v28, v28, v228
	v_mul_f32_e32 v29, v29, v229
	v_mul_f32_e32 v30, v30, v230
	v_mul_f32_e32 v31, v31, v231
	v_cvt_pk_bf16_f32 v118, v24, v25
	v_cvt_pk_bf16_f32 v119, v26, v27
	v_cvt_pk_bf16_f32 v120, v28, v29
	v_cvt_pk_bf16_f32 v121, v30, v31
	v_lshlrev_b32_e32 v24, 16, v106
	v_and_b32_e32 v25, 0xffff0000, v106
	v_lshlrev_b32_e32 v26, 16, v107
	v_and_b32_e32 v27, 0xffff0000, v107
	v_lshlrev_b32_e32 v28, 16, v108
	v_and_b32_e32 v29, 0xffff0000, v108
	v_lshlrev_b32_e32 v30, 16, v109
	v_and_b32_e32 v31, 0xffff0000, v109
	v_mul_f32_e32 v24, v24, v169
	v_mul_f32_e32 v25, v25, v169
	v_mul_f32_e32 v26, v26, v169
	v_mul_f32_e32 v27, v27, v169
	v_mul_f32_e32 v28, v28, v169
	v_mul_f32_e32 v29, v29, v169
	v_mul_f32_e32 v30, v30, v169
	v_mul_f32_e32 v31, v31, v169
	v_mul_f32_e32 v24, v24, v232
	v_mul_f32_e32 v25, v25, v233
	v_mul_f32_e32 v26, v26, v234
	v_mul_f32_e32 v27, v27, v235
	v_mul_f32_e32 v28, v28, v236
	v_mul_f32_e32 v29, v29, v237
	v_mul_f32_e32 v30, v30, v238
	v_mul_f32_e32 v31, v31, v239
	v_cvt_pk_bf16_f32 v106, v24, v25
	v_cvt_pk_bf16_f32 v107, v26, v27
	v_cvt_pk_bf16_f32 v108, v28, v29
	v_cvt_pk_bf16_f32 v109, v30, v31
	v_lshlrev_b32_e32 v24, 16, v102
	v_and_b32_e32 v25, 0xffff0000, v102
	v_lshlrev_b32_e32 v26, 16, v103
	v_and_b32_e32 v27, 0xffff0000, v103
	v_lshlrev_b32_e32 v28, 16, v104
	v_and_b32_e32 v29, 0xffff0000, v104
	v_lshlrev_b32_e32 v30, 16, v105
	v_and_b32_e32 v31, 0xffff0000, v105
	v_mul_f32_e32 v24, v24, v169
	v_mul_f32_e32 v25, v25, v169
	v_mul_f32_e32 v26, v26, v169
	v_mul_f32_e32 v27, v27, v169
	v_mul_f32_e32 v28, v28, v169
	v_mul_f32_e32 v29, v29, v169
	v_mul_f32_e32 v30, v30, v169
	v_mul_f32_e32 v31, v31, v169
	v_mul_f32_e32 v24, v24, v240
	v_mul_f32_e32 v25, v25, v241
	v_mul_f32_e32 v26, v26, v242
	v_mul_f32_e32 v27, v27, v243
	v_mul_f32_e32 v28, v28, v244
	v_mul_f32_e32 v29, v29, v245
	v_mul_f32_e32 v30, v30, v246
	v_mul_f32_e32 v31, v31, v247
	v_cvt_pk_bf16_f32 v102, v24, v25
	v_cvt_pk_bf16_f32 v103, v26, v27
	v_cvt_pk_bf16_f32 v104, v28, v29
	v_cvt_pk_bf16_f32 v105, v30, v31
	v_lshlrev_b32_e32 v24, 16, v98
	v_and_b32_e32 v25, 0xffff0000, v98
	v_lshlrev_b32_e32 v26, 16, v99
	v_and_b32_e32 v27, 0xffff0000, v99
	v_lshlrev_b32_e32 v28, 16, v100
	v_and_b32_e32 v29, 0xffff0000, v100
	v_lshlrev_b32_e32 v30, 16, v101
	v_and_b32_e32 v31, 0xffff0000, v101
	v_mul_f32_e32 v24, v24, v169
	v_mul_f32_e32 v25, v25, v169
	v_mul_f32_e32 v26, v26, v169
	v_mul_f32_e32 v27, v27, v169
	v_mul_f32_e32 v28, v28, v169
	v_mul_f32_e32 v29, v29, v169
	v_mul_f32_e32 v30, v30, v169
	v_mul_f32_e32 v31, v31, v169
	v_mul_f32_e32 v24, v24, v248
	v_mul_f32_e32 v25, v25, v249
	v_mul_f32_e32 v26, v26, v250
	v_mul_f32_e32 v27, v27, v251
	v_mul_f32_e32 v28, v28, v164
	v_mul_f32_e32 v29, v29, v165
	v_mul_f32_e32 v30, v30, v166
	v_mul_f32_e32 v31, v31, v167
	v_cvt_pk_bf16_f32 v98, v24, v25
	v_cvt_pk_bf16_f32 v99, v26, v27
	v_cvt_pk_bf16_f32 v100, v28, v29
	v_cvt_pk_bf16_f32 v101, v30, v31
	v_bitop3_b32 v0, v96, v54, v55 bitop3:0xde
	v_add_u32_e32 v174, 0, v0
	s_waitcnt lgkmcnt(0)
	s_barrier
	ds_read_b128 v[0:3], v174 offset:32768
	ds_read_b128 v[16:19], v174 offset:40960
	s_waitcnt vmcnt(7) lgkmcnt(1)
	v_mfma_f32_32x32x16_bf16 v[0:15], v[0:3], v[114:117], 0
	ds_read_b128 v[34:37], v176 offset:32768
	ds_read_b128 v[38:41], v176 offset:40960
	v_and_b32_e32 v60, 63, v58
	s_add_i32 s3, 0, 0x10000
	v_lshlrev_b32_e32 v61, 3, v60
	s_mov_b64 s[4:5], 0xa000
	s_cmp_lg_u32 0, -1
	v_cmp_gt_u32_e64 s[42:43], 32, v60
	s_waitcnt lgkmcnt(2)
	v_mfma_f32_32x32x16_bf16 v[16:31], v[16:19], v[114:117], 0
	s_waitcnt vmcnt(6) lgkmcnt(1)
	v_mfma_f32_32x32x16_bf16 v[0:15], v[34:37], v[110:113], v[0:15]
	v_or_b32_e32 v34, 64, v96
	v_bitop3_b32 v34, v34, v54, v55 bitop3:0xde
	v_add_u32_e32 v175, 0, v34
	s_waitcnt lgkmcnt(0)
	v_mfma_f32_32x32x16_bf16 v[16:31], v[38:41], v[110:113], v[16:31]
	ds_read_b128 v[34:37], v175 offset:32768
	ds_read_b128 v[38:41], v175 offset:40960
	s_waitcnt vmcnt(5) lgkmcnt(1)
	v_mfma_f32_32x32x16_bf16 v[0:15], v[34:37], v[122:125], v[0:15]
	v_or_b32_e32 v34, 0x60, v96
	v_bitop3_b32 v34, v34, v54, v55 bitop3:0xde
	v_add_u32_e32 v173, 0, v34
	s_waitcnt lgkmcnt(0)
	v_mfma_f32_32x32x16_bf16 v[16:31], v[38:41], v[122:125], v[16:31]
	ds_read_b128 v[34:37], v173 offset:32768
	ds_read_b128 v[38:41], v173 offset:40960
	s_waitcnt vmcnt(4) lgkmcnt(1)
	v_mfma_f32_32x32x16_bf16 v[0:15], v[34:37], v[126:129], v[0:15]
	v_or_b32_e32 v34, 0x80, v96
	v_bitop3_b32 v34, v34, v54, v55 bitop3:0xde
	v_add_u32_e32 v172, 0, v34
	s_waitcnt lgkmcnt(0)
	v_mfma_f32_32x32x16_bf16 v[16:31], v[38:41], v[126:129], v[16:31]
	ds_read_b128 v[34:37], v172 offset:32768
	ds_read_b128 v[38:41], v172 offset:40960
	s_waitcnt vmcnt(3) lgkmcnt(1)
	v_mfma_f32_32x32x16_bf16 v[0:15], v[34:37], v[118:121], v[0:15]
	v_or_b32_e32 v34, 0xa0, v96
	v_bitop3_b32 v34, v34, v54, v55 bitop3:0xde
	v_add_u32_e32 v170, 0, v34
	s_waitcnt lgkmcnt(0)
	v_mfma_f32_32x32x16_bf16 v[16:31], v[38:41], v[118:121], v[16:31]
	ds_read_b128 v[34:37], v170 offset:32768
	ds_read_b128 v[38:41], v170 offset:40960
	s_waitcnt vmcnt(2) lgkmcnt(1)
	v_mfma_f32_32x32x16_bf16 v[0:15], v[34:37], v[106:109], v[0:15]
	v_or_b32_e32 v34, 0xc0, v96
	v_bitop3_b32 v34, v34, v54, v55 bitop3:0xde
	v_add_u32_e32 v171, 0, v34
	ds_read_b128 v[34:37], v171 offset:32768
	v_bitop3_b32 v54, v56, v54, v55 bitop3:0xde
	v_add_u32_e32 v177, 0, v54
	s_waitcnt lgkmcnt(1)
	v_mfma_f32_32x32x16_bf16 v[16:31], v[38:41], v[106:109], v[16:31]
	ds_read_b128 v[38:41], v171 offset:40960
	global_load_dwordx4 v[42:45], v[42:43], off
	s_nop 0
	global_load_dwordx4 v[46:49], v[46:47], off
	s_waitcnt vmcnt(3) lgkmcnt(1)
	v_mfma_f32_32x32x16_bf16 v[0:15], v[34:37], v[102:105], v[0:15]
	global_load_dwordx4 v[34:37], v[50:51], off
	s_nop 0
	global_load_dwordx4 v[50:53], v[52:53], off
	ds_read_b128 v[54:57], v177 offset:32768
	s_waitcnt lgkmcnt(1)
	v_mfma_f32_32x32x16_bf16 v[16:31], v[38:41], v[102:105], v[16:31]
	v_and_b32_e32 v38, 0x3fffffc0, v58
	v_lshl_add_u32 v164, v38, 2, s3
	v_and_b32_e32 v38, 0xc0, v59
	v_and_or_b32 v59, v61, 24, v38
	ds_read_b128 v[38:41], v177 offset:40960
	s_cselect_b32 s3, 0, 0
	v_lshl_add_u32 v165, v163, 2, v164
	s_waitcnt vmcnt(4) lgkmcnt(1)
	v_mfma_f32_32x32x16_bf16 v[0:15], v[54:57], v[98:101], v[0:15]
	v_lshlrev_b32_e32 v54, 1, v58
	v_and_b32_e32 v54, 32, v54
	v_and_b32_e32 v55, 0x100, v61
	v_or3_b32 v187, v59, v54, v55
	v_lshl_add_u64 v[54:55], v[32:33], 0, s[12:13]
	v_lshl_add_u64 v[56:57], s[44:45], 0, v[54:55]
	v_add_u32_e32 v169, s3, v187
	s_waitcnt lgkmcnt(0)
	v_mfma_f32_32x32x16_bf16 v[16:31], v[38:41], v[98:101], v[16:31]
	s_nop 2
	v_max_f32_e32 v38, v1, v1
	v_max_f32_e32 v39, v0, v0
	v_max_f32_e32 v38, v39, v38
	v_max3_f32 v38, v38, v2, v3
	v_max3_f32 v38, v38, v4, v5
	v_max3_f32 v38, v38, v6, v7
	v_max3_f32 v38, v38, v8, v9
	v_max3_f32 v38, v38, v10, v11
	v_max3_f32 v38, v38, v12, v13
	v_max3_f32 v58, v38, v14, v15
	v_lshl_add_u64 v[38:39], v[32:33], 0, s[4:5]
	v_lshl_add_u64 v[40:41], s[44:45], 0, v[38:39]
	v_lshl_add_u64 v[38:39], s[48:49], 0, v[38:39]
	global_load_dwordx4 v[146:149], v[40:41], off
	global_load_dwordx4 v[150:153], v[56:57], off
	v_lshl_add_u64 v[40:41], s[48:49], 0, v[54:55]
	global_load_dwordx4 v[154:157], v[38:39], off
	global_load_dwordx4 v[158:161], v[40:41], off
	v_max3_f32 v38, v58, v16, v17
	v_max3_f32 v38, v38, v18, v19
	v_max3_f32 v38, v38, v20, v21
	v_max3_f32 v38, v38, v22, v23
	v_max3_f32 v38, v38, v24, v25
	v_max3_f32 v38, v38, v26, v27
	v_max3_f32 v38, v38, v28, v29
	v_max3_f32 v38, v38, v30, v31
	v_mov_b32_e32 v39, v38
	s_nop 1
	v_permlane32_swap_b32_e32 v38, v39
	v_max_f32_e32 v39, v39, v39
	v_max_f32_e32 v38, v38, v38
	v_max_f32_e32 v38, v38, v39
	v_add_f32_e32 v39, 0x7149f2ca, v38
	v_cmp_ge_f32_e32 vcc, s35, v39
	s_cmp_eq_u64 vcc, exec
	v_max_f32_e32 v189, 0xf149f2ca, v38
	s_cselect_b64 s[40:41], -1, 0
	v_cndmask_b32_e64 v188, v189, v206, s[40:41]
	s_waitcnt vmcnt(4)
	s_waitcnt vmcnt(7)
	ds_write_b128 v184, v[42:45] offset:16384
	s_waitcnt vmcnt(6)
	ds_write_b128 v185, v[46:49] offset:16384
	s_waitcnt vmcnt(5)
	ds_write_b128 v182, v[34:37] offset:49152
	s_waitcnt vmcnt(4)
	ds_write_b128 v183, v[50:53] offset:49152
	v_mul_f32_e32 v34, 0xbe0293ee, v188
	v_fmamk_f32 v0, v0, 0x3e0293ee, v34
	v_exp_f32_e32 v35, v0
	v_fmamk_f32 v0, v1, 0x3e0293ee, v34
	v_exp_f32_e32 v36, v0
	v_fmamk_f32 v0, v2, 0x3e0293ee, v34
	v_exp_f32_e32 v37, v0
	v_fmamk_f32 v0, v3, 0x3e0293ee, v34
	v_exp_f32_e32 v38, v0
	v_fmamk_f32 v0, v4, 0x3e0293ee, v34
	v_exp_f32_e32 v39, v0
	v_fmamk_f32 v0, v5, 0x3e0293ee, v34
	v_exp_f32_e32 v40, v0
	v_fmamk_f32 v0, v6, 0x3e0293ee, v34
	v_exp_f32_e32 v41, v0
	v_fmamk_f32 v0, v7, 0x3e0293ee, v34
	v_exp_f32_e32 v42, v0
	v_fmamk_f32 v0, v8, 0x3e0293ee, v34
	v_exp_f32_e32 v8, v0
	v_fmamk_f32 v0, v9, 0x3e0293ee, v34
	v_exp_f32_e32 v9, v0
	v_fmamk_f32 v0, v10, 0x3e0293ee, v34
	v_exp_f32_e32 v10, v0
	v_fmamk_f32 v0, v11, 0x3e0293ee, v34
	v_exp_f32_e32 v11, v0
	v_fmamk_f32 v0, v12, 0x3e0293ee, v34
	v_exp_f32_e32 v12, v0
	v_fmamk_f32 v0, v13, 0x3e0293ee, v34
	v_fmamk_f32 v16, v16, 0x3e0293ee, v34
	v_fmamk_f32 v17, v17, 0x3e0293ee, v34
	v_fmamk_f32 v18, v18, 0x3e0293ee, v34
	v_fmamk_f32 v19, v19, 0x3e0293ee, v34
	v_fmamk_f32 v20, v20, 0x3e0293ee, v34
	v_fmamk_f32 v21, v21, 0x3e0293ee, v34
	v_fmamk_f32 v22, v22, 0x3e0293ee, v34
	v_fmamk_f32 v23, v23, 0x3e0293ee, v34
	v_fmamk_f32 v24, v24, 0x3e0293ee, v34
	v_fmamk_f32 v25, v25, 0x3e0293ee, v34
	v_fmamk_f32 v26, v26, 0x3e0293ee, v34
	v_fmamk_f32 v27, v27, 0x3e0293ee, v34
	v_fmamk_f32 v28, v28, 0x3e0293ee, v34
	v_fmamk_f32 v29, v29, 0x3e0293ee, v34
	v_fmamk_f32 v30, v30, 0x3e0293ee, v34
	v_fmamk_f32 v31, v31, 0x3e0293ee, v34
	v_exp_f32_e32 v13, v0
	v_fmamk_f32 v0, v14, 0x3e0293ee, v34
	v_fmac_f32_e32 v34, 0x3e0293ee, v15
	v_exp_f32_e32 v14, v0
	v_exp_f32_e32 v15, v34
	s_waitcnt lgkmcnt(0)
	s_barrier
	ds_read_b128 v[0:3], v174 offset:49152
	ds_read_b128 v[4:7], v174 offset:57344
	s_waitcnt lgkmcnt(1)
	v_mfma_f32_32x32x16_bf16 v[80:95], v[0:3], v[114:117], 0
	s_waitcnt lgkmcnt(0)
	v_mfma_f32_32x32x16_bf16 v[64:79], v[4:7], v[114:117], 0
	ds_read_b128 v[0:3], v176 offset:49152
	ds_read_b128 v[4:7], v176 offset:57344
	s_waitcnt lgkmcnt(1)
	v_mfma_f32_32x32x16_bf16 v[80:95], v[0:3], v[110:113], v[80:95]
	s_waitcnt lgkmcnt(0)
	v_mfma_f32_32x32x16_bf16 v[64:79], v[4:7], v[110:113], v[64:79]
	ds_read_b128 v[0:3], v175 offset:49152
	ds_read_b128 v[4:7], v175 offset:57344
	s_waitcnt lgkmcnt(1)
	v_mfma_f32_32x32x16_bf16 v[80:95], v[0:3], v[122:125], v[80:95]
	s_waitcnt lgkmcnt(0)
	v_mfma_f32_32x32x16_bf16 v[64:79], v[4:7], v[122:125], v[64:79]
	ds_read_b128 v[0:3], v173 offset:49152
	ds_read_b128 v[4:7], v173 offset:57344
	s_waitcnt lgkmcnt(1)
	v_mfma_f32_32x32x16_bf16 v[80:95], v[0:3], v[126:129], v[80:95]
	s_waitcnt lgkmcnt(0)
	v_mfma_f32_32x32x16_bf16 v[64:79], v[4:7], v[126:129], v[64:79]
	ds_read_b128 v[0:3], v172 offset:49152
	ds_read_b128 v[4:7], v172 offset:57344
	s_waitcnt lgkmcnt(1)
	v_mfma_f32_32x32x16_bf16 v[80:95], v[0:3], v[118:121], v[80:95]
	s_waitcnt lgkmcnt(0)
	v_mfma_f32_32x32x16_bf16 v[64:79], v[4:7], v[118:121], v[64:79]
	ds_read_b128 v[0:3], v170 offset:49152
	ds_read_b128 v[4:7], v170 offset:57344
	s_waitcnt lgkmcnt(1)
	v_mfma_f32_32x32x16_bf16 v[80:95], v[0:3], v[106:109], v[80:95]
	s_waitcnt lgkmcnt(0)
	v_mfma_f32_32x32x16_bf16 v[64:79], v[4:7], v[106:109], v[64:79]
	ds_read_b128 v[0:3], v171 offset:49152
	ds_read_b128 v[4:7], v171 offset:57344
	s_waitcnt lgkmcnt(1)
	v_mfma_f32_32x32x16_bf16 v[80:95], v[0:3], v[102:105], v[80:95]
	s_waitcnt lgkmcnt(0)
	v_mfma_f32_32x32x16_bf16 v[64:79], v[4:7], v[102:105], v[64:79]
	ds_read_b128 v[0:3], v177 offset:49152
	ds_read_b128 v[4:7], v177 offset:57344
	v_cvt_pk_bf16_f32 v48, v35, v36
	v_cvt_pk_bf16_f32 v49, v37, v38
	v_cvt_pk_bf16_f32 v50, v39, v40
	v_cvt_pk_bf16_f32 v51, v41, v42
	v_cvt_pk_bf16_f32 v190, v8, v9
	v_cvt_pk_bf16_f32 v191, v10, v11
	s_waitcnt lgkmcnt(1)
	v_mfma_f32_32x32x16_bf16 v[80:95], v[0:3], v[98:101], v[80:95]
	v_exp_f32_e32 v0, v16
	v_exp_f32_e32 v16, v24
	v_add_f32_e32 v24, 0, v35
	v_add_f32_e32 v24, v36, v24
	v_add_f32_e32 v24, v37, v24
	v_add_f32_e32 v24, v38, v24
	v_add_f32_e32 v24, v39, v24
	v_add_f32_e32 v24, v40, v24
	v_add_f32_e32 v24, v41, v24
	v_add_f32_e32 v24, v42, v24
	v_add_f32_e32 v24, v8, v24
	v_add_f32_e32 v24, v9, v24
	v_add_f32_e32 v24, v10, v24
	v_add_f32_e32 v24, v11, v24
	v_add_f32_e32 v24, v12, v24
	v_exp_f32_e32 v1, v17
	v_add_f32_e32 v24, v13, v24
	v_exp_f32_e32 v2, v18
	v_add_f32_e32 v24, v14, v24
	v_exp_f32_e32 v3, v19
	v_add_f32_e32 v24, v15, v24
	s_waitcnt lgkmcnt(0)
	v_mfma_f32_32x32x16_bf16 v[64:79], v[4:7], v[98:101], v[64:79]
	v_exp_f32_e32 v4, v20
	v_add_f32_e32 v24, v0, v24
	v_exp_f32_e32 v5, v21
	v_add_f32_e32 v24, v1, v24
	v_exp_f32_e32 v6, v22
	v_add_f32_e32 v24, v2, v24
	v_exp_f32_e32 v7, v23
	v_add_f32_e32 v24, v3, v24
	v_add_f32_e32 v24, v4, v24
	v_exp_f32_e32 v17, v25
	v_add_f32_e32 v24, v5, v24
	v_exp_f32_e32 v18, v26
	v_add_f32_e32 v24, v6, v24
	v_exp_f32_e32 v19, v27
	v_add_f32_e32 v24, v7, v24
	v_exp_f32_e32 v20, v28
	v_add_f32_e32 v24, v16, v24
	v_exp_f32_e32 v21, v29
	v_add_f32_e32 v24, v17, v24
	v_exp_f32_e32 v22, v30
	v_add_f32_e32 v24, v18, v24
	v_exp_f32_e32 v23, v31
	v_add_f32_e32 v24, v19, v24
	v_add_f32_e32 v24, v20, v24
	v_add_f32_e32 v24, v21, v24
	v_add_f32_e32 v24, v22, v24
	v_add_f32_e32 v166, v23, v24
	v_mov_b32_e32 v167, v166
	v_cvt_pk_bf16_f32 v192, v12, v13
	s_nop 1
	v_permlane32_swap_b32_e32 v166, v167
	v_permlane32_swap_b32_e32 v48, v50
	v_permlane32_swap_b32_e32 v49, v51
	v_cvt_pk_bf16_f32 v193, v14, v15
	v_permlane32_swap_b32_e32 v190, v192
	v_cvt_pk_bf16_f32 v194, v0, v1
	v_cvt_pk_bf16_f32 v195, v2, v3
	v_cvt_pk_bf16_f32 v196, v4, v5
	v_cvt_pk_bf16_f32 v197, v6, v7
	v_cvt_pk_bf16_f32 v198, v16, v17
	v_cvt_pk_bf16_f32 v199, v18, v19
	v_cvt_pk_bf16_f32 v200, v20, v21
	v_cvt_pk_bf16_f32 v201, v22, v23
	v_permlane32_swap_b32_e32 v191, v193
	v_permlane32_swap_b32_e32 v194, v196
	v_permlane32_swap_b32_e32 v195, v197
	v_permlane32_swap_b32_e32 v198, v200
	v_permlane32_swap_b32_e32 v199, v201
	s_mov_b64 s[4:5], 0xc000
	v_lshl_add_u64 v[0:1], v[32:33], 0, s[4:5]
	s_mov_b64 s[4:5], 0xe000
	v_lshl_add_u64 v[2:3], s[48:49], 0, v[0:1]
	v_lshl_add_u64 v[4:5], v[32:33], 0, s[4:5]
	v_lshl_add_u64 v[0:1], s[44:45], 0, v[0:1]
	v_lshl_add_u64 v[6:7], s[48:49], 0, v[4:5]
	global_load_dwordx4 v[130:133], v[2:3], off
	global_load_dwordx4 v[134:137], v[6:7], off
	v_lshl_add_u64 v[2:3], s[44:45], 0, v[4:5]
	global_load_dwordx4 v[138:141], v[0:1], off
	global_load_dwordx4 v[142:145], v[2:3], off
	ds_read_b64_tr_b16 v[0:1], v169 offset:0
	ds_read_b64_tr_b16 v[2:3], v169 offset:0x800
	ds_read_b64_tr_b16 v[16:17], v169 offset:0x1000
	ds_read_b64_tr_b16 v[18:19], v169 offset:0x1800
	ds_read_b64_tr_b16 v[20:21], v169 offset:0x2000
	ds_read_b64_tr_b16 v[22:23], v169 offset:0x2800
	ds_read_b64_tr_b16 v[24:25], v169 offset:0x3000
	ds_read_b64_tr_b16 v[26:27], v169 offset:0x3800
	s_waitcnt lgkmcnt(0)
	s_nop 0
	v_mfma_f32_32x32x16_bf16 v[0:15], v[48:51], v[0:3], 0
	v_mfma_f32_32x32x16_bf16 v[0:15], v[190:193], v[16:19], v[0:15]
	ds_read_b64_tr_b16 v[16:17], v169 offset:0x200
	ds_read_b64_tr_b16 v[18:19], v169 offset:0xa00
	ds_read_b64_tr_b16 v[32:33], v169 offset:0x1200
	ds_read_b64_tr_b16 v[34:35], v169 offset:0x1a00
	ds_read_b64_tr_b16 v[36:37], v169 offset:0x2200
	ds_read_b64_tr_b16 v[38:39], v169 offset:0x2a00
	ds_read_b64_tr_b16 v[40:41], v169 offset:0x3200
	v_mfma_f32_32x32x16_bf16 v[0:15], v[194:197], v[20:23], v[0:15]
	ds_read_b64_tr_b16 v[42:43], v169 offset:0x3a00
	s_waitcnt lgkmcnt(0)
	v_mfma_f32_32x32x16_bf16 v[0:15], v[198:201], v[24:27], v[0:15]
	v_mfma_f32_32x32x16_bf16 v[16:31], v[48:51], v[16:19], 0
	v_mfma_f32_32x32x16_bf16 v[16:31], v[190:193], v[32:35], v[16:31]
	ds_read_b64_tr_b16 v[32:33], v169 offset:0x400
	ds_read_b64_tr_b16 v[34:35], v169 offset:0xc00
	ds_read_b64_tr_b16 v[52:53], v169 offset:0x1400
	ds_read_b64_tr_b16 v[54:55], v169 offset:0x1c00
	ds_read_b64_tr_b16 v[56:57], v169 offset:0x2400
	ds_read_b64_tr_b16 v[58:59], v169 offset:0x2c00
	ds_read_b64_tr_b16 v[60:61], v169 offset:0x3400
	v_mfma_f32_32x32x16_bf16 v[16:31], v[194:197], v[36:39], v[16:31]
	ds_read_b64_tr_b16 v[62:63], v169 offset:0x3c00
	s_waitcnt lgkmcnt(0)
	v_mfma_f32_32x32x16_bf16 v[16:31], v[198:201], v[40:43], v[16:31]
	v_mfma_f32_32x32x16_bf16 v[32:47], v[48:51], v[32:35], 0
	v_mfma_f32_32x32x16_bf16 v[32:47], v[190:193], v[52:55], v[32:47]
	ds_read_b64_tr_b16 v[52:53], v169 offset:0x600
	ds_read_b64_tr_b16 v[54:55], v169 offset:0xe00
	ds_read_b64_tr_b16 v[224:225], v169 offset:0x1600
	ds_read_b64_tr_b16 v[226:227], v169 offset:0x1e00
	ds_read_b64_tr_b16 v[228:229], v169 offset:0x2600
	ds_read_b64_tr_b16 v[230:231], v169 offset:0x2e00
	ds_read_b64_tr_b16 v[232:233], v169 offset:0x3600
	v_mfma_f32_32x32x16_bf16 v[32:47], v[194:197], v[56:59], v[32:47]
	ds_read_b64_tr_b16 v[234:235], v169 offset:0x3e00
	s_waitcnt lgkmcnt(0)
	v_mfma_f32_32x32x16_bf16 v[32:47], v[198:201], v[60:63], v[32:47]
	v_mfma_f32_32x32x16_bf16 v[48:63], v[48:51], v[52:55], 0
	v_max_f32_e32 v168, v81, v81
	s_barrier
	s_waitcnt vmcnt(4)
	s_waitcnt vmcnt(4)
	ds_write_b128 v184, v[158:161]
	ds_write_b128 v185, v[154:157]
	ds_write_b128 v182, v[150:153] offset:32768
	ds_write_b128 v183, v[146:149] offset:32768
	v_mfma_f32_32x32x16_bf16 v[48:63], v[190:193], v[224:227], v[48:63]
	v_max_f32_e32 v190, v80, v80
	v_max_f32_e32 v168, v190, v168
	v_max3_f32 v168, v168, v82, v83
	v_max3_f32 v168, v168, v84, v85
	v_max3_f32 v168, v168, v86, v87
	v_max3_f32 v168, v168, v88, v89
	v_max3_f32 v168, v168, v90, v91
	v_max3_f32 v168, v168, v92, v93
	v_max3_f32 v168, v168, v94, v95
	v_max3_f32 v168, v168, v64, v65
	v_max3_f32 v168, v168, v66, v67
	v_max3_f32 v168, v168, v68, v69
	v_max3_f32 v168, v168, v70, v71
	v_max3_f32 v168, v168, v72, v73
	v_max3_f32 v168, v168, v74, v75
	v_mfma_f32_32x32x16_bf16 v[48:63], v[194:197], v[228:231], v[48:63]
	v_max3_f32 v168, v168, v76, v77
	v_max3_f32 v168, v168, v78, v79
	v_mov_b32_e32 v190, v168
	s_nop 1
	v_permlane32_swap_b32_e32 v168, v190
	v_max_f32_e32 v190, v190, v190
	v_max_f32_e32 v168, v168, v168
	v_max_f32_e32 v168, v168, v190
	v_sub_f32_e32 v190, v168, v188
	v_cmp_ge_f32_e32 vcc, s35, v190
	v_max_f32_e32 v190, v188, v168
	v_mfma_f32_32x32x16_bf16 v[48:63], v[198:201], v[232:235], v[48:63]
	v_sub_f32_e32 v168, v188, v190
	v_mul_f32_e32 v168, 0x3e0293ee, v168
	v_exp_f32_e32 v168, v168
	s_cmp_eq_u64 vcc, exec
	s_cselect_b64 s[44:45], -1, 0
	v_cndmask_b32_e64 v168, v168, 1.0, s[44:45]
	v_cmp_gt_f32_e32 vcc, 1.0, v168
	s_cbranch_vccz .LBB0_897
	s_and_saveexec_b64 s[48:49], s[42:43]
	ds_write_b32 v165, v168 offset:128
	s_or_b64 exec, exec, s[48:49]
	s_waitcnt lgkmcnt(0)
	v_add_u32_e32 v158, v164, v96
	ds_read_b128 v[146:149], v158 offset:224
	ds_read_b128 v[150:153], v158 offset:192
	ds_read_b128 v[154:157], v158 offset:160
	ds_read_b128 v[158:161], v158 offset:128
	v_mov_b32_e32 v222, 9
	s_waitcnt lgkmcnt(3)
	v_pk_mul_f32 v[12:13], v[12:13], v[146:147]
	s_waitcnt lgkmcnt(2)
	v_pk_mul_f32 v[8:9], v[8:9], v[150:151]
	s_waitcnt lgkmcnt(1)
	v_pk_mul_f32 v[4:5], v[4:5], v[154:155]
	v_pk_mul_f32 v[14:15], v[14:15], v[148:149]
	v_pk_mul_f32 v[10:11], v[10:11], v[152:153]
	v_pk_mul_f32 v[6:7], v[6:7], v[156:157]
	s_waitcnt lgkmcnt(0)
	v_pk_mul_f32 v[2:3], v[2:3], v[160:161]
	v_pk_mul_f32 v[0:1], v[0:1], v[158:159]
	v_pk_mul_f32 v[28:29], v[28:29], v[146:147]
	v_pk_mul_f32 v[24:25], v[24:25], v[150:151]
	v_pk_mul_f32 v[20:21], v[20:21], v[154:155]
	v_pk_mul_f32 v[30:31], v[30:31], v[148:149]
	v_pk_mul_f32 v[26:27], v[26:27], v[152:153]
	v_pk_mul_f32 v[22:23], v[22:23], v[156:157]
	v_pk_mul_f32 v[18:19], v[18:19], v[160:161]
	v_pk_mul_f32 v[16:17], v[16:17], v[158:159]
	v_pk_mul_f32 v[44:45], v[44:45], v[146:147]
	v_pk_mul_f32 v[40:41], v[40:41], v[150:151]
	v_pk_mul_f32 v[36:37], v[36:37], v[154:155]
	v_pk_mul_f32 v[46:47], v[46:47], v[148:149]
	v_pk_mul_f32 v[42:43], v[42:43], v[152:153]
	v_pk_mul_f32 v[38:39], v[38:39], v[156:157]
	v_pk_mul_f32 v[34:35], v[34:35], v[160:161]
	v_pk_mul_f32 v[32:33], v[32:33], v[158:159]
	v_pk_mul_f32 v[60:61], v[60:61], v[146:147]
	v_pk_mul_f32 v[56:57], v[56:57], v[150:151]
	v_pk_mul_f32 v[52:53], v[52:53], v[154:155]
	v_pk_mul_f32 v[62:63], v[62:63], v[148:149]
	v_pk_mul_f32 v[58:59], v[58:59], v[152:153]
	v_pk_mul_f32 v[54:55], v[54:55], v[156:157]
	v_pk_mul_f32 v[50:51], v[50:51], v[160:161]
	v_pk_mul_f32 v[48:49], v[48:49], v[158:159]
	s_branch .LBB0_898

.LBB0_909:
	s_lshr_b32 s2, s67, 4
	s_ashr_i32 s42, s67, 7
	s_bfe_u32 s3, s2, 0x10002
	s_ashr_i32 s43, s42, 31
	s_lshl_b32 s2, s67, 8
	s_lshl_b64 s[4:5], s[42:43], 12
	s_and_b32 s2, s2, 0xf00
	s_bfe_u32 s10, s67, 0x30004
	s_or_b32 s2, s4, s2
	s_add_u32 s4, s2, 0x1000
	s_addc_u32 s5, s5, 0
	s_lshl_b32 s2, s42, 1
	s_or_b32 s11, s2, s3
	s_lshl_b64 s[44:45], s[4:5], 10
	s_mul_i32 s4, s4, 0xc00
	s_add_u32 s4, s4, 0x3000000
	s_add_u32 s4, s39, s4
	s_addc_u32 s5, s52, 0
	s_lshl_b32 s2, s10, 7
	s_lshl_b32 s10, s10, 8
	s_add_u32 s50, s4, s10
	s_addc_u32 s51, s5, 0
	s_mul_hi_u32 s4, s11, 0x110000
	s_mul_i32 s5, s43, 0x110000
	v_mov_b32_e32 v74, v204
	s_add_i32 s4, s4, s5
	s_mul_i32 s11, s11, 0x110000
	s_add_u32 s48, s61, s11
	s_waitcnt vmcnt(5)
	v_ashrrev_i32_e32 v16, 4, v74
	s_waitcnt vmcnt(4)
	v_lshlrev_b32_e32 v22, 3, v74
	v_add_u32_e32 v18, 32, v16
	s_addc_u32 s49, s62, s4
	s_waitcnt vmcnt(0)
	v_and_b32_e32 v0, 0x78, v22
	v_ashrrev_i32_e32 v17, 31, v16
	v_ashrrev_i32_e32 v19, 31, v18
	s_add_u32 s40, s63, s11
	v_lshlrev_b32_e32 v23, 1, v0
	s_waitcnt vmcnt(3)
	v_lshlrev_b64 v[48:49], 8, v[16:17]
	v_lshlrev_b64 v[12:13], 8, v[18:19]
	s_addc_u32 s41, s64, s4
	v_or_b32_e32 v50, v48, v23
	v_mov_b32_e32 v51, v49
	v_or_b32_e32 v12, v12, v23
	v_lshl_add_u64 v[0:1], s[40:41], 0, v[50:51]
	v_lshl_add_u64 v[4:5], s[40:41], 0, v[12:13]
	global_load_dwordx4 v[0:3], v[0:1], off
	s_nop 0
	global_load_dwordx4 v[4:7], v[4:5], off
	v_lshl_add_u64 v[8:9], s[48:49], 0, v[50:51]
	v_lshl_add_u64 v[12:13], s[48:49], 0, v[12:13]
	global_load_dwordx4 v[8:11], v[8:9], off
	v_ashrrev_i32_e32 v52, 1, v74
	global_load_dwordx4 v[12:15], v[12:13], off
	s_movk_i32 s4, 0xffe0
	v_bfi_b32 v20, s4, v52, v74
	v_ashrrev_i32_e32 v21, 31, v20
	v_bfe_u32 v186, v74, 5, 1
	v_mul_u32_u24_e32 v20, 0xc00, v20
	v_lshl_add_u64 v[20:21], s[50:51], 0, v[20:21]
	v_lshlrev_b32_e32 v96, 4, v186
	v_lshl_add_u64 v[20:21], v[20:21], 0, v[96:97]
	global_load_dwordx4 v[118:121], v[20:21], off
	global_load_dwordx4 v[114:117], v[20:21], off offset:32
	global_load_dwordx4 v[126:129], v[20:21], off offset:64
	global_load_dwordx4 v[122:125], v[20:21], off offset:96
	global_load_dwordx4 v[110:113], v[20:21], off offset:128
	global_load_dwordx4 v[106:109], v[20:21], off offset:160
	global_load_dwordx4 v[102:105], v[20:21], off offset:192
	global_load_dwordx4 v[98:101], v[20:21], off offset:224
	v_and_b32_e32 v19, 0xfffff0, v16
	v_lshlrev_b32_e32 v24, 1, v16
	v_lshrrev_b32_e32 v25, 1, v16
	v_and_b32_e32 v26, 3, v16
	v_and_or_b32 v19, v24, 8, v19
	v_and_or_b32 v24, v25, 4, v26
	v_and_b32_e32 v25, 0xfffff0, v18
	v_lshlrev_b32_e32 v26, 1, v18
	v_bfe_u32 v22, v22, 5, 2
	v_lshrrev_b32_e32 v19, 1, v19
	v_and_or_b32 v25, v26, 8, v25
	v_or_b32_e32 v19, v19, v22
	v_lshrrev_b32_e32 v25, 1, v25
	v_lshlrev_b32_e32 v24, 6, v24
	v_and_b32_e32 v27, 48, v23
	v_lshlrev_b32_e32 v19, 9, v19
	v_or_b32_e32 v22, v25, v22
	v_or3_b32 v19, v19, v24, v27
	v_lshlrev_b32_e32 v22, 9, v22
	v_or3_b32 v22, v22, v24, v27
	v_add_u32_e32 v192, 0, v19
	v_and_b32_e32 v17, 0x70, v74
	v_lshlrev_b32_e32 v16, 8, v16
	v_add_u32_e32 v193, 0, v22
	s_waitcnt vmcnt(0)
	v_bitop3_b32 v16, v23, v16, v17 bitop3:0xde
	v_and_b32_e32 v187, 31, v74
	v_lshlrev_b32_e32 v53, 4, v74
	v_add_u32_e32 v194, 0, v16
	s_add_i32 s5, 0, 0x10000
	s_mov_b64 s[10:11], 0x4000
	v_and_b32_e32 v182, 0xffffffe0, v52
	v_and_b32_e32 v75, 63, v74
	s_cmp_lg_u32 0, -1
	s_mul_i32 s4, s3, 0x110000
	s_waitcnt vmcnt(11)
	ds_write_b128 v192, v[0:3]
	s_waitcnt vmcnt(10)
	ds_write_b128 v193, v[4:7]
	v_lshlrev_b32_e32 v0, 8, v18
	v_bitop3_b32 v0, v23, v0, v17 bitop3:0xde
	v_add_u32_e32 v195, 0, v0
	s_waitcnt vmcnt(9)
	ds_write_b128 v194, v[8:11] offset:32768
	s_waitcnt vmcnt(8)
	ds_write_b128 v195, v[12:15] offset:32768
	s_load_dwordx2 s[100:101], s[88:89], 0x80
	v_lshlrev_b32_e32 v175, 5, v186
	v_mov_b32_e32 v188, s44
	v_lshrrev_b32_e32 v188, 10, v188
	v_lshrrev_b32_e32 v189, 1, v74
	v_and_b32_e32 v189, 0xffe0, v189
	v_and_or_b32 v189, v74, 31, v189
	v_add_u32_e32 v188, v188, v189
	v_bfe_u32 v94, v188, 6, 6
	v_and_b32_e32 v95, 63, v188
	v_cvt_f32_ubyte0_e32 v94, v94
	v_cvt_f32_ubyte0_e32 v95, v95
	v_lshlrev_b32_e32 v190, 4, v186
	v_add_u32_e32 v191, 0, v190
	v_cvt_f32_ubyte0_e32 v78, v191
	v_add_u32_e32 v191, 2, v190
	v_cvt_f32_ubyte0_e32 v79, v191
	v_add_u32_e32 v191, 4, v190
	v_cvt_f32_ubyte0_e32 v80, v191
	v_add_u32_e32 v191, 6, v190
	v_cvt_f32_ubyte0_e32 v81, v191
	v_add_u32_e32 v191, 8, v190
	v_cvt_f32_ubyte0_e32 v82, v191
	v_add_u32_e32 v191, 10, v190
	v_cvt_f32_ubyte0_e32 v83, v191
	v_add_u32_e32 v191, 12, v190
	v_cvt_f32_ubyte0_e32 v84, v191
	v_add_u32_e32 v191, 14, v190
	v_cvt_f32_ubyte0_e32 v85, v191
	v_add_u32_e32 v191, 32, v190
	v_cvt_f32_ubyte0_e32 v86, v191
	v_add_u32_e32 v191, 34, v190
	v_cvt_f32_ubyte0_e32 v87, v191
	v_add_u32_e32 v191, 36, v190
	v_cvt_f32_ubyte0_e32 v88, v191
	v_add_u32_e32 v191, 38, v190
	v_cvt_f32_ubyte0_e32 v89, v191
	v_add_u32_e32 v191, 40, v190
	v_cvt_f32_ubyte0_e32 v90, v191
	v_add_u32_e32 v191, 42, v190
	v_cvt_f32_ubyte0_e32 v91, v191
	v_add_u32_e32 v191, 44, v190
	v_cvt_f32_ubyte0_e32 v92, v191
	v_add_u32_e32 v191, 46, v190
	v_cvt_f32_ubyte0_e32 v93, v191
	v_mul_f32_e32 v78, 0xbe549a78, v78
	v_mul_f32_e32 v79, 0xbe549a78, v79
	v_mul_f32_e32 v80, 0xbe549a78, v80
	v_mul_f32_e32 v81, 0xbe549a78, v81
	v_mul_f32_e32 v82, 0xbe549a78, v82
	v_mul_f32_e32 v83, 0xbe549a78, v83
	v_mul_f32_e32 v84, 0xbe549a78, v84
	v_mul_f32_e32 v85, 0xbe549a78, v85
	v_mul_f32_e32 v86, 0xbe549a78, v86
	v_mul_f32_e32 v87, 0xbe549a78, v87
	v_mul_f32_e32 v88, 0xbe549a78, v88
	v_mul_f32_e32 v89, 0xbe549a78, v89
	v_mul_f32_e32 v90, 0xbe549a78, v90
	v_mul_f32_e32 v91, 0xbe549a78, v91
	v_mul_f32_e32 v92, 0xbe549a78, v92
	v_mul_f32_e32 v93, 0xbe549a78, v93
	v_exp_f32_e32 v78, v78
	v_exp_f32_e32 v79, v79
	v_exp_f32_e32 v80, v80
	v_exp_f32_e32 v81, v81
	v_exp_f32_e32 v82, v82
	v_exp_f32_e32 v83, v83
	v_exp_f32_e32 v84, v84
	v_exp_f32_e32 v85, v85
	v_exp_f32_e32 v86, v86
	v_exp_f32_e32 v87, v87
	v_exp_f32_e32 v88, v88
	v_exp_f32_e32 v89, v89
	v_exp_f32_e32 v90, v90
	v_exp_f32_e32 v91, v91
	v_exp_f32_e32 v92, v92
	v_exp_f32_e32 v93, v93
	s_waitcnt lgkmcnt(0)
	global_load_dwordx4 v[130:133], v175, s[100:101] offset:0
	global_load_dwordx4 v[134:137], v175, s[100:101] offset:16
	global_load_dwordx4 v[138:141], v175, s[100:101] offset:64
	global_load_dwordx4 v[142:145], v175, s[100:101] offset:80
	global_load_dwordx4 v[146:149], v175, s[100:101] offset:128
	global_load_dwordx4 v[150:153], v175, s[100:101] offset:144
	global_load_dwordx4 v[154:157], v175, s[100:101] offset:192
	global_load_dwordx4 v[158:161], v175, s[100:101] offset:208
	global_load_dwordx4 v[224:227], v175, s[100:101] offset:256
	global_load_dwordx4 v[228:231], v175, s[100:101] offset:272
	global_load_dwordx4 v[232:235], v175, s[100:101] offset:320
	global_load_dwordx4 v[236:239], v175, s[100:101] offset:336
	global_load_dwordx4 v[240:243], v175, s[100:101] offset:384
	global_load_dwordx4 v[244:247], v175, s[100:101] offset:400
	global_load_dwordx4 v[248:251], v175, s[100:101] offset:448
	global_load_dwordx4 v[164:167], v175, s[100:101] offset:464
	v_lshlrev_b32_e32 v24, 16, v118
	v_and_b32_e32 v25, 0xffff0000, v118
	v_lshlrev_b32_e32 v26, 16, v119
	v_and_b32_e32 v27, 0xffff0000, v119
	v_lshlrev_b32_e32 v28, 16, v120
	v_and_b32_e32 v29, 0xffff0000, v120
	v_lshlrev_b32_e32 v30, 16, v121
	v_and_b32_e32 v31, 0xffff0000, v121
	v_mul_f32_e32 v168, v24, v24
	v_fmac_f32_e32 v168, v25, v25
	v_fmac_f32_e32 v168, v26, v26
	v_fmac_f32_e32 v168, v27, v27
	v_fmac_f32_e32 v168, v28, v28
	v_fmac_f32_e32 v168, v29, v29
	v_fmac_f32_e32 v168, v30, v30
	v_fmac_f32_e32 v168, v31, v31
	v_lshlrev_b32_e32 v24, 16, v114
	v_and_b32_e32 v25, 0xffff0000, v114
	v_lshlrev_b32_e32 v26, 16, v115
	v_and_b32_e32 v27, 0xffff0000, v115
	v_lshlrev_b32_e32 v28, 16, v116
	v_and_b32_e32 v29, 0xffff0000, v116
	v_lshlrev_b32_e32 v30, 16, v117
	v_and_b32_e32 v31, 0xffff0000, v117
	v_fmac_f32_e32 v168, v24, v24
	v_fmac_f32_e32 v168, v25, v25
	v_fmac_f32_e32 v168, v26, v26
	v_fmac_f32_e32 v168, v27, v27
	v_fmac_f32_e32 v168, v28, v28
	v_fmac_f32_e32 v168, v29, v29
	v_fmac_f32_e32 v168, v30, v30
	v_fmac_f32_e32 v168, v31, v31
	v_lshlrev_b32_e32 v24, 16, v126
	v_and_b32_e32 v25, 0xffff0000, v126
	v_lshlrev_b32_e32 v26, 16, v127
	v_and_b32_e32 v27, 0xffff0000, v127
	v_lshlrev_b32_e32 v28, 16, v128
	v_and_b32_e32 v29, 0xffff0000, v128
	v_lshlrev_b32_e32 v30, 16, v129
	v_and_b32_e32 v31, 0xffff0000, v129
	v_fmac_f32_e32 v168, v24, v24
	v_fmac_f32_e32 v168, v25, v25
	v_fmac_f32_e32 v168, v26, v26
	v_fmac_f32_e32 v168, v27, v27
	v_fmac_f32_e32 v168, v28, v28
	v_fmac_f32_e32 v168, v29, v29
	v_fmac_f32_e32 v168, v30, v30
	v_fmac_f32_e32 v168, v31, v31
	v_lshlrev_b32_e32 v24, 16, v122
	v_and_b32_e32 v25, 0xffff0000, v122
	v_lshlrev_b32_e32 v26, 16, v123
	v_and_b32_e32 v27, 0xffff0000, v123
	v_lshlrev_b32_e32 v28, 16, v124
	v_and_b32_e32 v29, 0xffff0000, v124
	v_lshlrev_b32_e32 v30, 16, v125
	v_and_b32_e32 v31, 0xffff0000, v125
	v_fmac_f32_e32 v168, v24, v24
	v_fmac_f32_e32 v168, v25, v25
	v_fmac_f32_e32 v168, v26, v26
	v_fmac_f32_e32 v168, v27, v27
	v_fmac_f32_e32 v168, v28, v28
	v_fmac_f32_e32 v168, v29, v29
	v_fmac_f32_e32 v168, v30, v30
	v_fmac_f32_e32 v168, v31, v31
	v_lshlrev_b32_e32 v24, 16, v110
	v_and_b32_e32 v25, 0xffff0000, v110
	v_lshlrev_b32_e32 v26, 16, v111
	v_and_b32_e32 v27, 0xffff0000, v111
	v_lshlrev_b32_e32 v28, 16, v112
	v_and_b32_e32 v29, 0xffff0000, v112
	v_lshlrev_b32_e32 v30, 16, v113
	v_and_b32_e32 v31, 0xffff0000, v113
	v_fmac_f32_e32 v168, v24, v24
	v_fmac_f32_e32 v168, v25, v25
	v_fmac_f32_e32 v168, v26, v26
	v_fmac_f32_e32 v168, v27, v27
	v_fmac_f32_e32 v168, v28, v28
	v_fmac_f32_e32 v168, v29, v29
	v_fmac_f32_e32 v168, v30, v30
	v_fmac_f32_e32 v168, v31, v31
	v_lshlrev_b32_e32 v24, 16, v106
	v_and_b32_e32 v25, 0xffff0000, v106
	v_lshlrev_b32_e32 v26, 16, v107
	v_and_b32_e32 v27, 0xffff0000, v107
	v_lshlrev_b32_e32 v28, 16, v108
	v_and_b32_e32 v29, 0xffff0000, v108
	v_lshlrev_b32_e32 v30, 16, v109
	v_and_b32_e32 v31, 0xffff0000, v109
	v_fmac_f32_e32 v168, v24, v24
	v_fmac_f32_e32 v168, v25, v25
	v_fmac_f32_e32 v168, v26, v26
	v_fmac_f32_e32 v168, v27, v27
	v_fmac_f32_e32 v168, v28, v28
	v_fmac_f32_e32 v168, v29, v29
	v_fmac_f32_e32 v168, v30, v30
	v_fmac_f32_e32 v168, v31, v31
	v_lshlrev_b32_e32 v24, 16, v102
	v_and_b32_e32 v25, 0xffff0000, v102
	v_lshlrev_b32_e32 v26, 16, v103
	v_and_b32_e32 v27, 0xffff0000, v103
	v_lshlrev_b32_e32 v28, 16, v104
	v_and_b32_e32 v29, 0xffff0000, v104
	v_lshlrev_b32_e32 v30, 16, v105
	v_and_b32_e32 v31, 0xffff0000, v105
	v_fmac_f32_e32 v168, v24, v24
	v_fmac_f32_e32 v168, v25, v25
	v_fmac_f32_e32 v168, v26, v26
	v_fmac_f32_e32 v168, v27, v27
	v_fmac_f32_e32 v168, v28, v28
	v_fmac_f32_e32 v168, v29, v29
	v_fmac_f32_e32 v168, v30, v30
	v_fmac_f32_e32 v168, v31, v31
	v_lshlrev_b32_e32 v24, 16, v98
	v_and_b32_e32 v25, 0xffff0000, v98
	v_lshlrev_b32_e32 v26, 16, v99
	v_and_b32_e32 v27, 0xffff0000, v99
	v_lshlrev_b32_e32 v28, 16, v100
	v_and_b32_e32 v29, 0xffff0000, v100
	v_lshlrev_b32_e32 v30, 16, v101
	v_and_b32_e32 v31, 0xffff0000, v101
	v_fmac_f32_e32 v168, v24, v24
	v_fmac_f32_e32 v168, v25, v25
	v_fmac_f32_e32 v168, v26, v26
	v_fmac_f32_e32 v168, v27, v27
	v_fmac_f32_e32 v168, v28, v28
	v_fmac_f32_e32 v168, v29, v29
	v_fmac_f32_e32 v168, v30, v30
	v_fmac_f32_e32 v168, v31, v31
	v_mov_b32_e32 v170, v168
	s_nop 1
	v_permlane32_swap_b32_e32 v168, v170
	v_add_f32_e32 v168, v168, v170
	v_fmamk_f32 v168, v168, 0x3c000000, v207
	v_rsq_f32_e32 v169, v168
	s_nop 0
	v_mul_f32_e32 v170, v168, v169
	v_fma_f32 v170, -v170, v169, 1.0
	v_mul_f32_e32 v170, 0.5, v170
	v_fmac_f32_e32 v169, v169, v170
	s_waitcnt vmcnt(0)
	v_lshlrev_b32_e32 v24, 16, v118
	v_and_b32_e32 v25, 0xffff0000, v118
	v_lshlrev_b32_e32 v26, 16, v119
	v_and_b32_e32 v27, 0xffff0000, v119
	v_lshlrev_b32_e32 v28, 16, v120
	v_and_b32_e32 v29, 0xffff0000, v120
	v_lshlrev_b32_e32 v30, 16, v121
	v_and_b32_e32 v31, 0xffff0000, v121
	v_lshlrev_b32_e32 v34, 16, v126
	v_and_b32_e32 v35, 0xffff0000, v126
	v_lshlrev_b32_e32 v36, 16, v127
	v_and_b32_e32 v37, 0xffff0000, v127
	v_lshlrev_b32_e32 v38, 16, v128
	v_and_b32_e32 v39, 0xffff0000, v128
	v_lshlrev_b32_e32 v40, 16, v129
	v_and_b32_e32 v41, 0xffff0000, v129
	v_mul_f32_e32 v24, v24, v169
	v_mul_f32_e32 v25, v25, v169
	v_mul_f32_e32 v26, v26, v169
	v_mul_f32_e32 v27, v27, v169
	v_mul_f32_e32 v28, v28, v169
	v_mul_f32_e32 v29, v29, v169
	v_mul_f32_e32 v30, v30, v169
	v_mul_f32_e32 v31, v31, v169
	v_mul_f32_e32 v24, v24, v130
	v_mul_f32_e32 v25, v25, v131
	v_mul_f32_e32 v26, v26, v132
	v_mul_f32_e32 v27, v27, v133
	v_mul_f32_e32 v28, v28, v134
	v_mul_f32_e32 v29, v29, v135
	v_mul_f32_e32 v30, v30, v136
	v_mul_f32_e32 v31, v31, v137
	v_mul_f32_e32 v34, v34, v169
	v_mul_f32_e32 v35, v35, v169
	v_mul_f32_e32 v36, v36, v169
	v_mul_f32_e32 v37, v37, v169
	v_mul_f32_e32 v38, v38, v169
	v_mul_f32_e32 v39, v39, v169
	v_mul_f32_e32 v40, v40, v169
	v_mul_f32_e32 v41, v41, v169
	v_mul_f32_e32 v34, v34, v146
	v_mul_f32_e32 v35, v35, v147
	v_mul_f32_e32 v36, v36, v148
	v_mul_f32_e32 v37, v37, v149
	v_mul_f32_e32 v38, v38, v150
	v_mul_f32_e32 v39, v39, v151
	v_mul_f32_e32 v40, v40, v152
	v_mul_f32_e32 v41, v41, v153
	v_mul_f32_e32 v60, v78, v94
	v_mul_f32_e32 v61, v79, v94
	v_mul_f32_e32 v62, v80, v94
	v_mul_f32_e32 v63, v81, v94
	v_mul_f32_e32 v64, v82, v94
	v_mul_f32_e32 v65, v83, v94
	v_mul_f32_e32 v66, v84, v94
	v_mul_f32_e32 v67, v85, v94
	v_mul_f32_e32 v68, 0.15915494, v60
	v_mul_f32_e32 v69, 0.15915494, v61
	v_mul_f32_e32 v70, 0.15915494, v62
	v_mul_f32_e32 v71, 0.15915494, v63
	v_mul_f32_e32 v72, 0.15915494, v64
	v_mul_f32_e32 v73, 0.15915494, v65
	v_mul_f32_e32 v76, 0.15915494, v66
	v_mul_f32_e32 v77, 0.15915494, v67
	v_rndne_f32_e32 v68, v68
	v_rndne_f32_e32 v69, v69
	v_rndne_f32_e32 v70, v70
	v_rndne_f32_e32 v71, v71
	v_rndne_f32_e32 v72, v72
	v_rndne_f32_e32 v73, v73
	v_rndne_f32_e32 v76, v76
	v_rndne_f32_e32 v77, v77
	v_fmac_f32_e32 v60, 0xc0c90fdb, v68
	v_fmac_f32_e32 v61, 0xc0c90fdb, v69
	v_fmac_f32_e32 v62, 0xc0c90fdb, v70
	v_fmac_f32_e32 v63, 0xc0c90fdb, v71
	v_fmac_f32_e32 v64, 0xc0c90fdb, v72
	v_fmac_f32_e32 v65, 0xc0c90fdb, v73
	v_fmac_f32_e32 v66, 0xc0c90fdb, v76
	v_fmac_f32_e32 v67, 0xc0c90fdb, v77
	v_fmac_f32_e32 v60, 0x343bbd2e, v68
	v_fmac_f32_e32 v61, 0x343bbd2e, v69
	v_fmac_f32_e32 v62, 0x343bbd2e, v70
	v_fmac_f32_e32 v63, 0x343bbd2e, v71
	v_fmac_f32_e32 v64, 0x343bbd2e, v72
	v_fmac_f32_e32 v65, 0x343bbd2e, v73
	v_fmac_f32_e32 v66, 0x343bbd2e, v76
	v_fmac_f32_e32 v67, 0x343bbd2e, v77
	v_mul_f32_e32 v60, 0.15915494, v60
	v_mul_f32_e32 v61, 0.15915494, v61
	v_mul_f32_e32 v62, 0.15915494, v62
	v_mul_f32_e32 v63, 0.15915494, v63
	v_mul_f32_e32 v64, 0.15915494, v64
	v_mul_f32_e32 v65, 0.15915494, v65
	v_mul_f32_e32 v66, 0.15915494, v66
	v_mul_f32_e32 v67, 0.15915494, v67
	v_sin_f32_e32 v68, v60
	v_sin_f32_e32 v69, v61
	v_sin_f32_e32 v70, v62
	v_sin_f32_e32 v71, v63
	v_sin_f32_e32 v72, v64
	v_sin_f32_e32 v73, v65
	v_sin_f32_e32 v76, v66
	v_sin_f32_e32 v77, v67
	v_cos_f32_e32 v60, v60
	v_cos_f32_e32 v61, v61
	v_cos_f32_e32 v62, v62
	v_cos_f32_e32 v63, v63
	v_cos_f32_e32 v64, v64
	v_cos_f32_e32 v65, v65
	v_cos_f32_e32 v66, v66
	v_cos_f32_e32 v67, v67
	s_nop 0
	v_mul_f32_e32 v171, v68, v34
	v_mul_f32_e32 v172, v60, v34
	v_fmac_f32_e32 v172, v68, v24
	v_fma_f32 v24, v60, v24, -v171
	v_mov_b32_e32 v34, v172
	v_mul_f32_e32 v171, v69, v35
	v_mul_f32_e32 v172, v61, v35
	v_fmac_f32_e32 v172, v69, v25
	v_fma_f32 v25, v61, v25, -v171
	v_mov_b32_e32 v35, v172
	v_mul_f32_e32 v171, v70, v36
	v_mul_f32_e32 v172, v62, v36
	v_fmac_f32_e32 v172, v70, v26
	v_fma_f32 v26, v62, v26, -v171
	v_mov_b32_e32 v36, v172
	v_mul_f32_e32 v171, v71, v37
	v_mul_f32_e32 v172, v63, v37
	v_fmac_f32_e32 v172, v71, v27
	v_fma_f32 v27, v63, v27, -v171
	v_mov_b32_e32 v37, v172
	v_mul_f32_e32 v171, v72, v38
	v_mul_f32_e32 v172, v64, v38
	v_fmac_f32_e32 v172, v72, v28
	v_fma_f32 v28, v64, v28, -v171
	v_mov_b32_e32 v38, v172
	v_mul_f32_e32 v171, v73, v39
	v_mul_f32_e32 v172, v65, v39
	v_fmac_f32_e32 v172, v73, v29
	v_fma_f32 v29, v65, v29, -v171
	v_mov_b32_e32 v39, v172
	v_mul_f32_e32 v171, v76, v40
	v_mul_f32_e32 v172, v66, v40
	v_fmac_f32_e32 v172, v76, v30
	v_fma_f32 v30, v66, v30, -v171
	v_mov_b32_e32 v40, v172
	v_mul_f32_e32 v171, v77, v41
	v_mul_f32_e32 v172, v67, v41
	v_fmac_f32_e32 v172, v77, v31
	v_fma_f32 v31, v67, v31, -v171
	v_mov_b32_e32 v41, v172
	v_cvt_pk_bf16_f32 v118, v24, v25
	v_cvt_pk_bf16_f32 v119, v26, v27
	v_cvt_pk_bf16_f32 v120, v28, v29
	v_cvt_pk_bf16_f32 v121, v30, v31
	v_cvt_pk_bf16_f32 v126, v34, v35
	v_cvt_pk_bf16_f32 v127, v36, v37
	v_cvt_pk_bf16_f32 v128, v38, v39
	v_cvt_pk_bf16_f32 v129, v40, v41
	v_lshlrev_b32_e32 v24, 16, v114
	v_and_b32_e32 v25, 0xffff0000, v114
	v_lshlrev_b32_e32 v26, 16, v115
	v_and_b32_e32 v27, 0xffff0000, v115
	v_lshlrev_b32_e32 v28, 16, v116
	v_and_b32_e32 v29, 0xffff0000, v116
	v_lshlrev_b32_e32 v30, 16, v117
	v_and_b32_e32 v31, 0xffff0000, v117
	v_lshlrev_b32_e32 v34, 16, v122
	v_and_b32_e32 v35, 0xffff0000, v122
	v_lshlrev_b32_e32 v36, 16, v123
	v_and_b32_e32 v37, 0xffff0000, v123
	v_lshlrev_b32_e32 v38, 16, v124
	v_and_b32_e32 v39, 0xffff0000, v124
	v_lshlrev_b32_e32 v40, 16, v125
	v_and_b32_e32 v41, 0xffff0000, v125
	v_mul_f32_e32 v24, v24, v169
	v_mul_f32_e32 v25, v25, v169
	v_mul_f32_e32 v26, v26, v169
	v_mul_f32_e32 v27, v27, v169
	v_mul_f32_e32 v28, v28, v169
	v_mul_f32_e32 v29, v29, v169
	v_mul_f32_e32 v30, v30, v169
	v_mul_f32_e32 v31, v31, v169
	v_mul_f32_e32 v24, v24, v138
	v_mul_f32_e32 v25, v25, v139
	v_mul_f32_e32 v26, v26, v140
	v_mul_f32_e32 v27, v27, v141
	v_mul_f32_e32 v28, v28, v142
	v_mul_f32_e32 v29, v29, v143
	v_mul_f32_e32 v30, v30, v144
	v_mul_f32_e32 v31, v31, v145
	v_mul_f32_e32 v34, v34, v169
	v_mul_f32_e32 v35, v35, v169
	v_mul_f32_e32 v36, v36, v169
	v_mul_f32_e32 v37, v37, v169
	v_mul_f32_e32 v38, v38, v169
	v_mul_f32_e32 v39, v39, v169
	v_mul_f32_e32 v40, v40, v169
	v_mul_f32_e32 v41, v41, v169
	v_mul_f32_e32 v34, v34, v154
	v_mul_f32_e32 v35, v35, v155
	v_mul_f32_e32 v36, v36, v156
	v_mul_f32_e32 v37, v37, v157
	v_mul_f32_e32 v38, v38, v158
	v_mul_f32_e32 v39, v39, v159
	v_mul_f32_e32 v40, v40, v160
	v_mul_f32_e32 v41, v41, v161
	v_mul_f32_e32 v60, v86, v94
	v_mul_f32_e32 v61, v87, v94
	v_mul_f32_e32 v62, v88, v94
	v_mul_f32_e32 v63, v89, v94
	v_mul_f32_e32 v64, v90, v94
	v_mul_f32_e32 v65, v91, v94
	v_mul_f32_e32 v66, v92, v94
	v_mul_f32_e32 v67, v93, v94
	v_mul_f32_e32 v68, 0.15915494, v60
	v_mul_f32_e32 v69, 0.15915494, v61
	v_mul_f32_e32 v70, 0.15915494, v62
	v_mul_f32_e32 v71, 0.15915494, v63
	v_mul_f32_e32 v72, 0.15915494, v64
	v_mul_f32_e32 v73, 0.15915494, v65
	v_mul_f32_e32 v76, 0.15915494, v66
	v_mul_f32_e32 v77, 0.15915494, v67
	v_rndne_f32_e32 v68, v68
	v_rndne_f32_e32 v69, v69
	v_rndne_f32_e32 v70, v70
	v_rndne_f32_e32 v71, v71
	v_rndne_f32_e32 v72, v72
	v_rndne_f32_e32 v73, v73
	v_rndne_f32_e32 v76, v76
	v_rndne_f32_e32 v77, v77
	v_fmac_f32_e32 v60, 0xc0c90fdb, v68
	v_fmac_f32_e32 v61, 0xc0c90fdb, v69
	v_fmac_f32_e32 v62, 0xc0c90fdb, v70
	v_fmac_f32_e32 v63, 0xc0c90fdb, v71
	v_fmac_f32_e32 v64, 0xc0c90fdb, v72
	v_fmac_f32_e32 v65, 0xc0c90fdb, v73
	v_fmac_f32_e32 v66, 0xc0c90fdb, v76
	v_fmac_f32_e32 v67, 0xc0c90fdb, v77
	v_fmac_f32_e32 v60, 0x343bbd2e, v68
	v_fmac_f32_e32 v61, 0x343bbd2e, v69
	v_fmac_f32_e32 v62, 0x343bbd2e, v70
	v_fmac_f32_e32 v63, 0x343bbd2e, v71
	v_fmac_f32_e32 v64, 0x343bbd2e, v72
	v_fmac_f32_e32 v65, 0x343bbd2e, v73
	v_fmac_f32_e32 v66, 0x343bbd2e, v76
	v_fmac_f32_e32 v67, 0x343bbd2e, v77
	v_mul_f32_e32 v60, 0.15915494, v60
	v_mul_f32_e32 v61, 0.15915494, v61
	v_mul_f32_e32 v62, 0.15915494, v62
	v_mul_f32_e32 v63, 0.15915494, v63
	v_mul_f32_e32 v64, 0.15915494, v64
	v_mul_f32_e32 v65, 0.15915494, v65
	v_mul_f32_e32 v66, 0.15915494, v66
	v_mul_f32_e32 v67, 0.15915494, v67
	v_sin_f32_e32 v68, v60
	v_sin_f32_e32 v69, v61
	v_sin_f32_e32 v70, v62
	v_sin_f32_e32 v71, v63
	v_sin_f32_e32 v72, v64
	v_sin_f32_e32 v73, v65
	v_sin_f32_e32 v76, v66
	v_sin_f32_e32 v77, v67
	v_cos_f32_e32 v60, v60
	v_cos_f32_e32 v61, v61
	v_cos_f32_e32 v62, v62
	v_cos_f32_e32 v63, v63
	v_cos_f32_e32 v64, v64
	v_cos_f32_e32 v65, v65
	v_cos_f32_e32 v66, v66
	v_cos_f32_e32 v67, v67
	s_nop 0
	v_mul_f32_e32 v171, v68, v34
	v_mul_f32_e32 v172, v60, v34
	v_fmac_f32_e32 v172, v68, v24
	v_fma_f32 v24, v60, v24, -v171
	v_mov_b32_e32 v34, v172
	v_mul_f32_e32 v171, v69, v35
	v_mul_f32_e32 v172, v61, v35
	v_fmac_f32_e32 v172, v69, v25
	v_fma_f32 v25, v61, v25, -v171
	v_mov_b32_e32 v35, v172
	v_mul_f32_e32 v171, v70, v36
	v_mul_f32_e32 v172, v62, v36
	v_fmac_f32_e32 v172, v70, v26
	v_fma_f32 v26, v62, v26, -v171
	v_mov_b32_e32 v36, v172
	v_mul_f32_e32 v171, v71, v37
	v_mul_f32_e32 v172, v63, v37
	v_fmac_f32_e32 v172, v71, v27
	v_fma_f32 v27, v63, v27, -v171
	v_mov_b32_e32 v37, v172
	v_mul_f32_e32 v171, v72, v38
	v_mul_f32_e32 v172, v64, v38
	v_fmac_f32_e32 v172, v72, v28
	v_fma_f32 v28, v64, v28, -v171
	v_mov_b32_e32 v38, v172
	v_mul_f32_e32 v171, v73, v39
	v_mul_f32_e32 v172, v65, v39
	v_fmac_f32_e32 v172, v73, v29
	v_fma_f32 v29, v65, v29, -v171
	v_mov_b32_e32 v39, v172
	v_mul_f32_e32 v171, v76, v40
	v_mul_f32_e32 v172, v66, v40
	v_fmac_f32_e32 v172, v76, v30
	v_fma_f32 v30, v66, v30, -v171
	v_mov_b32_e32 v40, v172
	v_mul_f32_e32 v171, v77, v41
	v_mul_f32_e32 v172, v67, v41
	v_fmac_f32_e32 v172, v77, v31
	v_fma_f32 v31, v67, v31, -v171
	v_mov_b32_e32 v41, v172
	v_cvt_pk_bf16_f32 v114, v24, v25
	v_cvt_pk_bf16_f32 v115, v26, v27
	v_cvt_pk_bf16_f32 v116, v28, v29
	v_cvt_pk_bf16_f32 v117, v30, v31
	v_cvt_pk_bf16_f32 v122, v34, v35
	v_cvt_pk_bf16_f32 v123, v36, v37
	v_cvt_pk_bf16_f32 v124, v38, v39
	v_cvt_pk_bf16_f32 v125, v40, v41
	v_lshlrev_b32_e32 v24, 16, v110
	v_and_b32_e32 v25, 0xffff0000, v110
	v_lshlrev_b32_e32 v26, 16, v111
	v_and_b32_e32 v27, 0xffff0000, v111
	v_lshlrev_b32_e32 v28, 16, v112
	v_and_b32_e32 v29, 0xffff0000, v112
	v_lshlrev_b32_e32 v30, 16, v113
	v_and_b32_e32 v31, 0xffff0000, v113
	v_lshlrev_b32_e32 v34, 16, v102
	v_and_b32_e32 v35, 0xffff0000, v102
	v_lshlrev_b32_e32 v36, 16, v103
	v_and_b32_e32 v37, 0xffff0000, v103
	v_lshlrev_b32_e32 v38, 16, v104
	v_and_b32_e32 v39, 0xffff0000, v104
	v_lshlrev_b32_e32 v40, 16, v105
	v_and_b32_e32 v41, 0xffff0000, v105
	v_mul_f32_e32 v24, v24, v169
	v_mul_f32_e32 v25, v25, v169
	v_mul_f32_e32 v26, v26, v169
	v_mul_f32_e32 v27, v27, v169
	v_mul_f32_e32 v28, v28, v169
	v_mul_f32_e32 v29, v29, v169
	v_mul_f32_e32 v30, v30, v169
	v_mul_f32_e32 v31, v31, v169
	v_mul_f32_e32 v24, v24, v224
	v_mul_f32_e32 v25, v25, v225
	v_mul_f32_e32 v26, v26, v226
	v_mul_f32_e32 v27, v27, v227
	v_mul_f32_e32 v28, v28, v228
	v_mul_f32_e32 v29, v29, v229
	v_mul_f32_e32 v30, v30, v230
	v_mul_f32_e32 v31, v31, v231
	v_mul_f32_e32 v34, v34, v169
	v_mul_f32_e32 v35, v35, v169
	v_mul_f32_e32 v36, v36, v169
	v_mul_f32_e32 v37, v37, v169
	v_mul_f32_e32 v38, v38, v169
	v_mul_f32_e32 v39, v39, v169
	v_mul_f32_e32 v40, v40, v169
	v_mul_f32_e32 v41, v41, v169
	v_mul_f32_e32 v34, v34, v240
	v_mul_f32_e32 v35, v35, v241
	v_mul_f32_e32 v36, v36, v242
	v_mul_f32_e32 v37, v37, v243
	v_mul_f32_e32 v38, v38, v244
	v_mul_f32_e32 v39, v39, v245
	v_mul_f32_e32 v40, v40, v246
	v_mul_f32_e32 v41, v41, v247
	v_mul_f32_e32 v60, v78, v95
	v_mul_f32_e32 v61, v79, v95
	v_mul_f32_e32 v62, v80, v95
	v_mul_f32_e32 v63, v81, v95
	v_mul_f32_e32 v64, v82, v95
	v_mul_f32_e32 v65, v83, v95
	v_mul_f32_e32 v66, v84, v95
	v_mul_f32_e32 v67, v85, v95
	v_mul_f32_e32 v68, 0.15915494, v60
	v_mul_f32_e32 v69, 0.15915494, v61
	v_mul_f32_e32 v70, 0.15915494, v62
	v_mul_f32_e32 v71, 0.15915494, v63
	v_mul_f32_e32 v72, 0.15915494, v64
	v_mul_f32_e32 v73, 0.15915494, v65
	v_mul_f32_e32 v76, 0.15915494, v66
	v_mul_f32_e32 v77, 0.15915494, v67
	v_rndne_f32_e32 v68, v68
	v_rndne_f32_e32 v69, v69
	v_rndne_f32_e32 v70, v70
	v_rndne_f32_e32 v71, v71
	v_rndne_f32_e32 v72, v72
	v_rndne_f32_e32 v73, v73
	v_rndne_f32_e32 v76, v76
	v_rndne_f32_e32 v77, v77
	v_fmac_f32_e32 v60, 0xc0c90fdb, v68
	v_fmac_f32_e32 v61, 0xc0c90fdb, v69
	v_fmac_f32_e32 v62, 0xc0c90fdb, v70
	v_fmac_f32_e32 v63, 0xc0c90fdb, v71
	v_fmac_f32_e32 v64, 0xc0c90fdb, v72
	v_fmac_f32_e32 v65, 0xc0c90fdb, v73
	v_fmac_f32_e32 v66, 0xc0c90fdb, v76
	v_fmac_f32_e32 v67, 0xc0c90fdb, v77
	v_fmac_f32_e32 v60, 0x343bbd2e, v68
	v_fmac_f32_e32 v61, 0x343bbd2e, v69
	v_fmac_f32_e32 v62, 0x343bbd2e, v70
	v_fmac_f32_e32 v63, 0x343bbd2e, v71
	v_fmac_f32_e32 v64, 0x343bbd2e, v72
	v_fmac_f32_e32 v65, 0x343bbd2e, v73
	v_fmac_f32_e32 v66, 0x343bbd2e, v76
	v_fmac_f32_e32 v67, 0x343bbd2e, v77
	v_mul_f32_e32 v60, 0.15915494, v60
	v_mul_f32_e32 v61, 0.15915494, v61
	v_mul_f32_e32 v62, 0.15915494, v62
	v_mul_f32_e32 v63, 0.15915494, v63
	v_mul_f32_e32 v64, 0.15915494, v64
	v_mul_f32_e32 v65, 0.15915494, v65
	v_mul_f32_e32 v66, 0.15915494, v66
	v_mul_f32_e32 v67, 0.15915494, v67
	v_sin_f32_e32 v68, v60
	v_sin_f32_e32 v69, v61
	v_sin_f32_e32 v70, v62
	v_sin_f32_e32 v71, v63
	v_sin_f32_e32 v72, v64
	v_sin_f32_e32 v73, v65
	v_sin_f32_e32 v76, v66
	v_sin_f32_e32 v77, v67
	v_cos_f32_e32 v60, v60
	v_cos_f32_e32 v61, v61
	v_cos_f32_e32 v62, v62
	v_cos_f32_e32 v63, v63
	v_cos_f32_e32 v64, v64
	v_cos_f32_e32 v65, v65
	v_cos_f32_e32 v66, v66
	v_cos_f32_e32 v67, v67
	s_nop 0
	v_mul_f32_e32 v171, v68, v34
	v_mul_f32_e32 v172, v60, v34
	v_fmac_f32_e32 v172, v68, v24
	v_fma_f32 v24, v60, v24, -v171
	v_mov_b32_e32 v34, v172
	v_mul_f32_e32 v171, v69, v35
	v_mul_f32_e32 v172, v61, v35
	v_fmac_f32_e32 v172, v69, v25
	v_fma_f32 v25, v61, v25, -v171
	v_mov_b32_e32 v35, v172
	v_mul_f32_e32 v171, v70, v36
	v_mul_f32_e32 v172, v62, v36
	v_fmac_f32_e32 v172, v70, v26
	v_fma_f32 v26, v62, v26, -v171
	v_mov_b32_e32 v36, v172
	v_mul_f32_e32 v171, v71, v37
	v_mul_f32_e32 v172, v63, v37
	v_fmac_f32_e32 v172, v71, v27
	v_fma_f32 v27, v63, v27, -v171
	v_mov_b32_e32 v37, v172
	v_mul_f32_e32 v171, v72, v38
	v_mul_f32_e32 v172, v64, v38
	v_fmac_f32_e32 v172, v72, v28
	v_fma_f32 v28, v64, v28, -v171
	v_mov_b32_e32 v38, v172
	v_mul_f32_e32 v171, v73, v39
	v_mul_f32_e32 v172, v65, v39
	v_fmac_f32_e32 v172, v73, v29
	v_fma_f32 v29, v65, v29, -v171
	v_mov_b32_e32 v39, v172
	v_mul_f32_e32 v171, v76, v40
	v_mul_f32_e32 v172, v66, v40
	v_fmac_f32_e32 v172, v76, v30
	v_fma_f32 v30, v66, v30, -v171
	v_mov_b32_e32 v40, v172
	v_mul_f32_e32 v171, v77, v41
	v_mul_f32_e32 v172, v67, v41
	v_fmac_f32_e32 v172, v77, v31
	v_fma_f32 v31, v67, v31, -v171
	v_mov_b32_e32 v41, v172
	v_cvt_pk_bf16_f32 v110, v24, v25
	v_cvt_pk_bf16_f32 v111, v26, v27
	v_cvt_pk_bf16_f32 v112, v28, v29
	v_cvt_pk_bf16_f32 v113, v30, v31
	v_cvt_pk_bf16_f32 v102, v34, v35
	v_cvt_pk_bf16_f32 v103, v36, v37
	v_cvt_pk_bf16_f32 v104, v38, v39
	v_cvt_pk_bf16_f32 v105, v40, v41
	v_lshlrev_b32_e32 v24, 16, v106
	v_and_b32_e32 v25, 0xffff0000, v106
	v_lshlrev_b32_e32 v26, 16, v107
	v_and_b32_e32 v27, 0xffff0000, v107
	v_lshlrev_b32_e32 v28, 16, v108
	v_and_b32_e32 v29, 0xffff0000, v108
	v_lshlrev_b32_e32 v30, 16, v109
	v_and_b32_e32 v31, 0xffff0000, v109
	v_lshlrev_b32_e32 v34, 16, v98
	v_and_b32_e32 v35, 0xffff0000, v98
	v_lshlrev_b32_e32 v36, 16, v99
	v_and_b32_e32 v37, 0xffff0000, v99
	v_lshlrev_b32_e32 v38, 16, v100
	v_and_b32_e32 v39, 0xffff0000, v100
	v_lshlrev_b32_e32 v40, 16, v101
	v_and_b32_e32 v41, 0xffff0000, v101
	v_mul_f32_e32 v24, v24, v169
	v_mul_f32_e32 v25, v25, v169
	v_mul_f32_e32 v26, v26, v169
	v_mul_f32_e32 v27, v27, v169
	v_mul_f32_e32 v28, v28, v169
	v_mul_f32_e32 v29, v29, v169
	v_mul_f32_e32 v30, v30, v169
	v_mul_f32_e32 v31, v31, v169
	v_mul_f32_e32 v24, v24, v232
	v_mul_f32_e32 v25, v25, v233
	v_mul_f32_e32 v26, v26, v234
	v_mul_f32_e32 v27, v27, v235
	v_mul_f32_e32 v28, v28, v236
	v_mul_f32_e32 v29, v29, v237
	v_mul_f32_e32 v30, v30, v238
	v_mul_f32_e32 v31, v31, v239
	v_mul_f32_e32 v34, v34, v169
	v_mul_f32_e32 v35, v35, v169
	v_mul_f32_e32 v36, v36, v169
	v_mul_f32_e32 v37, v37, v169
	v_mul_f32_e32 v38, v38, v169
	v_mul_f32_e32 v39, v39, v169
	v_mul_f32_e32 v40, v40, v169
	v_mul_f32_e32 v41, v41, v169
	v_mul_f32_e32 v34, v34, v248
	v_mul_f32_e32 v35, v35, v249
	v_mul_f32_e32 v36, v36, v250
	v_mul_f32_e32 v37, v37, v251
	v_mul_f32_e32 v38, v38, v164
	v_mul_f32_e32 v39, v39, v165
	v_mul_f32_e32 v40, v40, v166
	v_mul_f32_e32 v41, v41, v167
	v_mul_f32_e32 v60, v86, v95
	v_mul_f32_e32 v61, v87, v95
	v_mul_f32_e32 v62, v88, v95
	v_mul_f32_e32 v63, v89, v95
	v_mul_f32_e32 v64, v90, v95
	v_mul_f32_e32 v65, v91, v95
	v_mul_f32_e32 v66, v92, v95
	v_mul_f32_e32 v67, v93, v95
	v_mul_f32_e32 v68, 0.15915494, v60
	v_mul_f32_e32 v69, 0.15915494, v61
	v_mul_f32_e32 v70, 0.15915494, v62
	v_mul_f32_e32 v71, 0.15915494, v63
	v_mul_f32_e32 v72, 0.15915494, v64
	v_mul_f32_e32 v73, 0.15915494, v65
	v_mul_f32_e32 v76, 0.15915494, v66
	v_mul_f32_e32 v77, 0.15915494, v67
	v_rndne_f32_e32 v68, v68
	v_rndne_f32_e32 v69, v69
	v_rndne_f32_e32 v70, v70
	v_rndne_f32_e32 v71, v71
	v_rndne_f32_e32 v72, v72
	v_rndne_f32_e32 v73, v73
	v_rndne_f32_e32 v76, v76
	v_rndne_f32_e32 v77, v77
	v_fmac_f32_e32 v60, 0xc0c90fdb, v68
	v_fmac_f32_e32 v61, 0xc0c90fdb, v69
	v_fmac_f32_e32 v62, 0xc0c90fdb, v70
	v_fmac_f32_e32 v63, 0xc0c90fdb, v71
	v_fmac_f32_e32 v64, 0xc0c90fdb, v72
	v_fmac_f32_e32 v65, 0xc0c90fdb, v73
	v_fmac_f32_e32 v66, 0xc0c90fdb, v76
	v_fmac_f32_e32 v67, 0xc0c90fdb, v77
	v_fmac_f32_e32 v60, 0x343bbd2e, v68
	v_fmac_f32_e32 v61, 0x343bbd2e, v69
	v_fmac_f32_e32 v62, 0x343bbd2e, v70
	v_fmac_f32_e32 v63, 0x343bbd2e, v71
	v_fmac_f32_e32 v64, 0x343bbd2e, v72
	v_fmac_f32_e32 v65, 0x343bbd2e, v73
	v_fmac_f32_e32 v66, 0x343bbd2e, v76
	v_fmac_f32_e32 v67, 0x343bbd2e, v77
	v_mul_f32_e32 v60, 0.15915494, v60
	v_mul_f32_e32 v61, 0.15915494, v61
	v_mul_f32_e32 v62, 0.15915494, v62
	v_mul_f32_e32 v63, 0.15915494, v63
	v_mul_f32_e32 v64, 0.15915494, v64
	v_mul_f32_e32 v65, 0.15915494, v65
	v_mul_f32_e32 v66, 0.15915494, v66
	v_mul_f32_e32 v67, 0.15915494, v67
	v_sin_f32_e32 v68, v60
	v_sin_f32_e32 v69, v61
	v_sin_f32_e32 v70, v62
	v_sin_f32_e32 v71, v63
	v_sin_f32_e32 v72, v64
	v_sin_f32_e32 v73, v65
	v_sin_f32_e32 v76, v66
	v_sin_f32_e32 v77, v67
	v_cos_f32_e32 v60, v60
	v_cos_f32_e32 v61, v61
	v_cos_f32_e32 v62, v62
	v_cos_f32_e32 v63, v63
	v_cos_f32_e32 v64, v64
	v_cos_f32_e32 v65, v65
	v_cos_f32_e32 v66, v66
	v_cos_f32_e32 v67, v67
	s_nop 0
	v_mul_f32_e32 v171, v68, v34
	v_mul_f32_e32 v172, v60, v34
	v_fmac_f32_e32 v172, v68, v24
	v_fma_f32 v24, v60, v24, -v171
	v_mov_b32_e32 v34, v172
	v_mul_f32_e32 v171, v69, v35
	v_mul_f32_e32 v172, v61, v35
	v_fmac_f32_e32 v172, v69, v25
	v_fma_f32 v25, v61, v25, -v171
	v_mov_b32_e32 v35, v172
	v_mul_f32_e32 v171, v70, v36
	v_mul_f32_e32 v172, v62, v36
	v_fmac_f32_e32 v172, v70, v26
	v_fma_f32 v26, v62, v26, -v171
	v_mov_b32_e32 v36, v172
	v_mul_f32_e32 v171, v71, v37
	v_mul_f32_e32 v172, v63, v37
	v_fmac_f32_e32 v172, v71, v27
	v_fma_f32 v27, v63, v27, -v171
	v_mov_b32_e32 v37, v172
	v_mul_f32_e32 v171, v72, v38
	v_mul_f32_e32 v172, v64, v38
	v_fmac_f32_e32 v172, v72, v28
	v_fma_f32 v28, v64, v28, -v171
	v_mov_b32_e32 v38, v172
	v_mul_f32_e32 v171, v73, v39
	v_mul_f32_e32 v172, v65, v39
	v_fmac_f32_e32 v172, v73, v29
	v_fma_f32 v29, v65, v29, -v171
	v_mov_b32_e32 v39, v172
	v_mul_f32_e32 v171, v76, v40
	v_mul_f32_e32 v172, v66, v40
	v_fmac_f32_e32 v172, v76, v30
	v_fma_f32 v30, v66, v30, -v171
	v_mov_b32_e32 v40, v172
	v_mul_f32_e32 v171, v77, v41
	v_mul_f32_e32 v172, v67, v41
	v_fmac_f32_e32 v172, v77, v31
	v_fma_f32 v31, v67, v31, -v171
	v_mov_b32_e32 v41, v172
	v_cvt_pk_bf16_f32 v106, v24, v25
	v_cvt_pk_bf16_f32 v107, v26, v27
	v_cvt_pk_bf16_f32 v108, v28, v29
	v_cvt_pk_bf16_f32 v109, v30, v31
	v_cvt_pk_bf16_f32 v98, v34, v35
	v_cvt_pk_bf16_f32 v99, v36, v37
	v_cvt_pk_bf16_f32 v100, v38, v39
	v_cvt_pk_bf16_f32 v101, v40, v41
	v_lshlrev_b32_e32 v12, 8, v187
	v_and_b32_e32 v13, 0x70, v53
	v_bitop3_b32 v0, v96, v12, v13 bitop3:0xde
	v_add_u32_e32 v196, 0, v0
	s_waitcnt lgkmcnt(0)
	s_barrier
	ds_read_b128 v[0:3], v196 offset:32768
	ds_read_b128 v[4:7], v196 offset:40960
	s_waitcnt vmcnt(7) lgkmcnt(1)
	v_mfma_f32_32x32x16_bf16 v[16:31], v[0:3], v[118:121], 0
	v_or_b32_e32 v0, 32, v96
	v_bitop3_b32 v0, v0, v12, v13 bitop3:0xde
	v_add_u32_e32 v201, 0, v0
	v_and_b32_e32 v15, 0xc0, v53
	v_lshlrev_b32_e32 v14, 3, v75
	s_mov_b32 s72, s73
	s_mov_b32 s74, s73
	s_waitcnt lgkmcnt(0)
	v_mfma_f32_32x32x16_bf16 v[32:47], v[4:7], v[118:121], 0
	ds_read_b128 v[0:3], v201 offset:32768
	ds_read_b128 v[4:7], v201 offset:40960
	s_mov_b32 s75, s73
	s_mov_b32 s76, s73
	s_mov_b32 s77, s73
	s_mov_b32 s78, s73
	s_mov_b32 s79, s73
	s_mov_b32 s80, s73
	s_waitcnt vmcnt(6) lgkmcnt(1)
	v_mfma_f32_32x32x16_bf16 v[16:31], v[0:3], v[114:117], v[16:31]
	v_or_b32_e32 v0, 64, v96
	v_bitop3_b32 v0, v0, v12, v13 bitop3:0xde
	v_add_u32_e32 v200, 0, v0
	s_mov_b32 s81, s73
	s_mov_b32 s82, s73
	s_mov_b32 s83, s73
	s_mov_b32 s84, s73
	s_waitcnt lgkmcnt(0)
	v_mfma_f32_32x32x16_bf16 v[32:47], v[4:7], v[114:117], v[32:47]
	ds_read_b128 v[0:3], v200 offset:32768
	ds_read_b128 v[4:7], v200 offset:40960
	s_mov_b32 s85, s73
	s_mov_b32 s86, s73
	s_mov_b32 s87, s73
	v_mov_b32_e32 v222, 9
	s_mov_b32 s3, 1
	v_mov_b32_e32 v189, 0
	s_waitcnt vmcnt(5) lgkmcnt(1)
	v_mfma_f32_32x32x16_bf16 v[16:31], v[0:3], v[126:129], v[16:31]
	v_or_b32_e32 v0, 0x60, v96
	v_bitop3_b32 v0, v0, v12, v13 bitop3:0xde
	v_add_u32_e32 v199, 0, v0
	s_waitcnt lgkmcnt(0)
	v_mfma_f32_32x32x16_bf16 v[32:47], v[4:7], v[126:129], v[32:47]
	ds_read_b128 v[0:3], v199 offset:32768
	ds_read_b128 v[4:7], v199 offset:40960
	s_waitcnt vmcnt(4) lgkmcnt(1)
	v_mfma_f32_32x32x16_bf16 v[16:31], v[0:3], v[122:125], v[16:31]
	v_or_b32_e32 v0, 0x80, v96
	v_bitop3_b32 v0, v0, v12, v13 bitop3:0xde
	v_add_u32_e32 v198, 0, v0
	s_waitcnt lgkmcnt(0)
	v_mfma_f32_32x32x16_bf16 v[32:47], v[4:7], v[122:125], v[32:47]
	ds_read_b128 v[0:3], v198 offset:32768
	ds_read_b128 v[4:7], v198 offset:40960
	s_waitcnt vmcnt(3) lgkmcnt(1)
	v_mfma_f32_32x32x16_bf16 v[16:31], v[0:3], v[110:113], v[16:31]
	v_or_b32_e32 v0, 0xa0, v96
	v_bitop3_b32 v0, v0, v12, v13 bitop3:0xde
	v_add_u32_e32 v197, 0, v0
	ds_read_b128 v[0:3], v197 offset:32768
	s_waitcnt lgkmcnt(1)
	v_mfma_f32_32x32x16_bf16 v[32:47], v[4:7], v[110:113], v[32:47]
	v_and_b32_e32 v4, 0x3fffffc0, v74
	v_lshl_add_u32 v183, v4, 2, s5
	ds_read_b128 v[4:7], v197 offset:40960
	s_cselect_b32 s5, 0, 0
	v_lshl_add_u32 v188, v187, 2, v183
	s_waitcnt vmcnt(2) lgkmcnt(1)
	v_mfma_f32_32x32x16_bf16 v[16:31], v[0:3], v[106:109], v[16:31]
	v_lshl_add_u64 v[0:1], v[50:51], 0, s[10:11]
	s_mov_b64 s[10:11], 0x6000
	v_lshl_add_u64 v[2:3], s[40:41], 0, v[0:1]
	v_lshl_add_u64 v[8:9], v[50:51], 0, s[10:11]
	v_lshl_add_u64 v[0:1], s[48:49], 0, v[0:1]
	v_lshl_add_u64 v[10:11], s[40:41], 0, v[8:9]
	global_load_dwordx4 v[52:55], v[2:3], off
	global_load_dwordx4 v[56:59], v[10:11], off
	v_lshl_add_u64 v[2:3], s[48:49], 0, v[8:9]
	global_load_dwordx4 v[60:63], v[0:1], off
	global_load_dwordx4 v[64:67], v[2:3], off
	v_or_b32_e32 v0, 0xc0, v96
	v_bitop3_b32 v0, v0, v12, v13 bitop3:0xde
	v_add_u32_e32 v203, 0, v0
	ds_read_b128 v[0:3], v203 offset:32768
	v_lshlrev_b32_e32 v9, 1, v74
	v_and_or_b32 v8, v14, 24, v15
	s_waitcnt lgkmcnt(1)
	v_mfma_f32_32x32x16_bf16 v[32:47], v[4:7], v[106:109], v[32:47]
	v_and_b32_e32 v4, 32, v9
	v_and_b32_e32 v5, 0x100, v14
	v_or3_b32 v76, v8, v4, v5
	ds_read_b128 v[4:7], v203 offset:40960
	s_mov_b64 s[10:11], 0xa000
	v_add_u32_e32 v191, s5, v76
	s_waitcnt vmcnt(5) lgkmcnt(1)
	v_mfma_f32_32x32x16_bf16 v[16:31], v[0:3], v[102:105], v[16:31]
	v_or_b32_e32 v0, 0xe0, v96
	v_bitop3_b32 v0, v0, v12, v13 bitop3:0xde
	v_add_u32_e32 v202, 0, v0
	ds_read_b128 v[0:3], v202 offset:32768
	ds_read_b128 v[68:71], v202 offset:40960
	s_waitcnt lgkmcnt(2)
	v_mfma_f32_32x32x16_bf16 v[32:47], v[4:7], v[102:105], v[32:47]
	s_waitcnt vmcnt(4) lgkmcnt(1)
	v_mfma_f32_32x32x16_bf16 v[16:31], v[0:3], v[98:101], v[16:31]
	v_mov_b64_e32 v[0:1], s[72:73]
	v_mov_b64_e32 v[14:15], s[86:87]
	v_mov_b64_e32 v[2:3], s[74:75]
	v_mov_b64_e32 v[4:5], s[76:77]
	v_mov_b64_e32 v[6:7], s[78:79]
	v_mov_b64_e32 v[8:9], s[80:81]
	v_mov_b64_e32 v[10:11], s[82:83]
	s_waitcnt lgkmcnt(0)
	v_mfma_f32_32x32x16_bf16 v[32:47], v[68:71], v[98:101], v[32:47]
	s_nop 2
	v_max_f32_e32 v68, v17, v17
	v_max_f32_e32 v69, v16, v16
	v_max_f32_e32 v68, v69, v68
	v_max3_f32 v68, v68, v18, v19
	v_max3_f32 v68, v68, v20, v21
	v_max3_f32 v68, v68, v22, v23
	v_max3_f32 v68, v68, v24, v25
	v_max3_f32 v68, v68, v26, v27
	v_max3_f32 v68, v68, v28, v29
	v_max3_f32 v68, v68, v30, v31
	v_max3_f32 v68, v68, v32, v33
	v_max3_f32 v68, v68, v34, v35
	v_max3_f32 v68, v68, v36, v37
	v_max3_f32 v68, v68, v38, v39
	v_max3_f32 v68, v68, v40, v41
	v_max3_f32 v68, v68, v42, v43
	v_max3_f32 v68, v68, v44, v45
	v_max3_f32 v77, v68, v46, v47
	v_lshl_add_u64 v[68:69], v[50:51], 0, s[10:11]
	v_lshl_add_u64 v[70:71], s[48:49], 0, v[68:69]
	v_lshl_add_u64 v[50:51], v[50:51], 0, s[12:13]
	v_lshl_add_u64 v[68:69], s[40:41], 0, v[68:69]
	v_lshl_add_u64 v[72:73], s[48:49], 0, v[50:51]
	global_load_dwordx4 v[138:141], v[70:71], off
	global_load_dwordx4 v[130:133], v[72:73], off
	v_lshl_add_u64 v[50:51], s[40:41], 0, v[50:51]
	global_load_dwordx4 v[142:145], v[68:69], off
	global_load_dwordx4 v[134:137], v[50:51], off
	v_mov_b32_e32 v78, v77
	s_nop 1
	v_permlane32_swap_b32_e32 v77, v78
	v_max_f32_e32 v50, v78, v78
	v_max_f32_e32 v51, v77, v77
	v_max_f32_e32 v50, v51, v50
	v_add_f32_e32 v51, 0x7149f2ca, v50
	v_cmp_ge_f32_e32 vcc, s35, v51
	s_cmp_eq_u64 vcc, exec
	v_max_f32_e32 v50, 0xf149f2ca, v50
	s_cselect_b64 vcc, -1, 0
	v_cndmask_b32_e32 v170, v50, v206, vcc
	v_sub_f32_e32 v51, 0xf149f2ca, v50
	v_mul_f32_e32 v50, 0xbe0293ee, v170
	v_fmamk_f32 v16, v16, 0x3e0293ee, v50
	v_exp_f32_e32 v163, v16
	v_fmamk_f32 v16, v17, 0x3e0293ee, v50
	v_exp_f32_e32 v177, v16
	v_fmamk_f32 v16, v18, 0x3e0293ee, v50
	v_exp_f32_e32 v164, v16
	v_fmamk_f32 v16, v19, 0x3e0293ee, v50
	v_exp_f32_e32 v227, v16
	v_fmamk_f32 v16, v20, 0x3e0293ee, v50
	v_exp_f32_e32 v176, v16
	v_fmamk_f32 v16, v21, 0x3e0293ee, v50
	v_exp_f32_e32 v230, v16
	v_fmamk_f32 v16, v22, 0x3e0293ee, v50
	v_exp_f32_e32 v165, v16
	v_fmamk_f32 v16, v23, 0x3e0293ee, v50
	v_exp_f32_e32 v175, v16
	v_fmamk_f32 v16, v24, 0x3e0293ee, v50
	v_mul_f32_e32 v51, 0x3e0293ee, v51
	v_exp_f32_e32 v166, v16
	v_fmamk_f32 v16, v25, 0x3e0293ee, v50
	v_exp_f32_e32 v51, v51
	v_exp_f32_e32 v173, v16
	v_fmamk_f32 v16, v26, 0x3e0293ee, v50
	v_exp_f32_e32 v167, v16
	v_fmamk_f32 v16, v27, 0x3e0293ee, v50
	v_exp_f32_e32 v174, v16
	v_fmamk_f32 v16, v28, 0x3e0293ee, v50
	s_addk_i32 s5, 0x4000
	s_mul_i32 s10, s42, 0x220000
	v_exp_f32_e32 v168, v16
	v_fmamk_f32 v16, v29, 0x3e0293ee, v50
	v_add_u32_e32 v190, s5, v76
	s_mul_hi_i32 s5, s42, 0x220000
	s_add_u32 s4, s10, s4
	v_pk_fma_f32 v[146:147], v[46:47], s[14:15], v[50:51] op_sel_hi:[1,0,0]
	v_pk_fma_f32 v[152:153], v[44:45], s[14:15], v[50:51] op_sel_hi:[1,0,0]
	v_pk_fma_f32 v[156:157], v[42:43], s[14:15], v[50:51] op_sel_hi:[1,0,0]
	v_pk_fma_f32 v[148:149], v[40:41], s[14:15], v[50:51] op_sel_hi:[1,0,0]
	v_pk_fma_f32 v[150:151], v[38:39], s[14:15], v[50:51] op_sel_hi:[1,0,0]
	v_pk_fma_f32 v[154:155], v[36:37], s[14:15], v[50:51] op_sel_hi:[1,0,0]
	v_pk_fma_f32 v[158:159], v[34:35], s[14:15], v[50:51] op_sel_hi:[1,0,0]
	v_pk_fma_f32 v[160:161], v[32:33], s[14:15], v[50:51] op_sel_hi:[1,0,0]
	v_exp_f32_e32 v171, v16
	v_fmamk_f32 v16, v30, 0x3e0293ee, v50
	v_fmac_f32_e32 v50, 0x3e0293ee, v31
	s_addc_u32 s5, s5, 0
	v_exp_f32_e32 v169, v16
	v_exp_f32_e32 v172, v50
	v_lshl_add_u64 v[16:17], s[4:5], 0, v[48:49]
	v_and_b32_e32 v18, 15, v74
	s_waitcnt vmcnt(4)
	v_lshl_or_b32 v16, v18, 4, v16
	v_mov_b64_e32 v[12:13], s[84:85]
	s_waitcnt vmcnt(7)
	ds_write_b128 v192, v[52:55] offset:16384
	s_waitcnt vmcnt(6)
	ds_write_b128 v193, v[56:59] offset:16384
	s_waitcnt vmcnt(5)
	ds_write_b128 v194, v[60:63] offset:49152
	s_waitcnt vmcnt(4)
	ds_write_b128 v195, v[64:67] offset:49152
	v_cndmask_b32_e64 v223, v51, 1.0, vcc
	v_lshl_add_u64 v[184:185], s[46:47], 0, v[16:17]
	v_mov_b64_e32 v[62:63], v[14:15]
	v_mov_b64_e32 v[46:47], v[14:15]
	v_mov_b64_e32 v[30:31], v[14:15]
	v_cmp_gt_u32_e64 s[40:41], 32, v75
	v_mov_b64_e32 v[60:61], v[12:13]
	v_mov_b64_e32 v[58:59], v[10:11]
	v_mov_b64_e32 v[56:57], v[8:9]
	v_mov_b64_e32 v[54:55], v[6:7]
	v_mov_b64_e32 v[52:53], v[4:5]
	v_mov_b64_e32 v[50:51], v[2:3]
	v_mov_b64_e32 v[48:49], v[0:1]
	v_mov_b64_e32 v[44:45], v[12:13]
	v_mov_b64_e32 v[42:43], v[10:11]
	v_mov_b64_e32 v[40:41], v[8:9]
	v_mov_b64_e32 v[38:39], v[6:7]
	v_mov_b64_e32 v[36:37], v[4:5]
	v_mov_b64_e32 v[34:35], v[2:3]
	v_mov_b64_e32 v[32:33], v[0:1]
	v_mov_b64_e32 v[28:29], v[12:13]
	v_mov_b64_e32 v[26:27], v[10:11]
	v_mov_b64_e32 v[24:25], v[8:9]
	v_mov_b64_e32 v[22:23], v[6:7]
	v_mov_b64_e32 v[20:21], v[4:5]
	v_mov_b64_e32 v[18:19], v[2:3]
	v_mov_b64_e32 v[16:17], v[0:1]
	s_waitcnt lgkmcnt(0)
	s_barrier
